# attention mainloop rewritten by hand (QK/PV MFMAs with neighbour-tile softmax fillers, LDS reads a block ahead, DMA two tiles ahead, constant ring offsets) + 16-row K swizzle removing 2-way LDS bank c
# speedup vs baseline: 1.0539x; 1.0539x over previous
; #define LAS __attribute__((address_space(3)))
; __device__ __forceinline__ const float* inp(int k) { const CAS cfptr* p = (const CAS cfptr*)__builtin_amdgcn_kernarg_segment_ptr(); asm volatile("" : "+s"(p)); return p[k]; }
; __device__ __forceinline__ int tid_() { int t = threadIdx.x; asm volatile("" : "+v"(t)); return t; }
; __device__ __forceinline__ int v_rd_base(int lane) { return ((lane & 3) << 3) | (((lane >> 2) & 3) << 6) | (((lane >> 4) & 1) << 5) | (((lane >> 5) & 1) << 8); }
; template <bool SHIFT> __device__ __forceinline__ void attn_dense_body(const bf16* __restrict__ Qb, const bf16* __restrict__ Kh, const bf16* __restrict__ Vh, bf16* __restrict__ Ob, int seq, char* lds, LAS unsigned char* ldsl, float negB, const float* __restrict__ gq, int qpos0) {
;     ...
;   const int vb0 = (int)(uintptr_t)V_lds + v_rd_base(lane);
;   const int widu = __builtin_amdgcn_readfirstlane(wid);
;   const int kr0 = 8 * wid + (lane >> 4), kr1 = kr0 + 4, kp = lane & 15;
;   const int vkk = 8 * wid + ((lane & 31) >> 2), vk = (vkk & ~0xC) | ((vkk & 4) << 1) | ((vkk & 8) >> 1), vcc = 32 * (lane >> 5) + 8 * (lane & 3);
;   const bf16* kg0 = Kh + (long)kr0 * LDK + ((kp ^ (kr0 & 7)) * 8); const bf16* kg1 = Kh + (long)kr1 * LDK + ((kp ^ (kr1 & 7)) * 8); const bf16* vg = Vh + (long)vk * LDV + vcc;
;   LAS unsigned char* const lV = ldsl; LAS unsigned char* const lK = ldsl + 3 * SHM_V;
;     ...
;   f32x16 pA0, pA1, pB0, pB1; bf16x8 pa0, pa1, pa2, pa3; const int NT = seq / KVBLK;
;   DMA(0, 0); asm volatile("s_waitcnt vmcnt(0)" ::: "memory"); __syncthreads();
; __global__ void __launch_bounds__(NWAVES * 64, 2) mk_fwd(Args args) {
;     ...
;         { const float* gq = inp(26); const float* gk = inp(27); const int l = tid_() & 63; float a = fabsf(gq[l]), c = fabsf(gk[l]);
;           if (l < 32) { a = fmaxf(a, fabsf(gq[64 + l])); c = fmaxf(c, fabsf(gk[64 + l])); }
; #pragma unroll
;           for (int o = 1; o < 64; o <<= 1) { a = fmaxf(a, __shfl_xor(a, o)); c = fmaxf(c, __shfl_xor(c, o)); }
;           negB = -(96.0f * 0.10206207261596575f * 1.4426950408889634f * 1.01f) * a * c;
;           negB = __uint_as_float(__builtin_amdgcn_readfirstlane(__float_as_uint(negB))); }
.LBB0_1587:
	s_or_b64 exec, exec, s[8:9]
	v_mbcnt_lo_u32_b32 v0, -1, 0
	v_mbcnt_hi_u32_b32 v0, -1, v0
	v_and_b32_e32 v3, 64, v0
	v_add_u32_e32 v3, 64, v3
	v_xor_b32_e32 v4, 1, v0
	v_cmp_lt_i32_e32 vcc, v4, v3
	s_ashr_i32 s9, s2, 31
	s_lshr_b32 s9, s9, 29
	v_cndmask_b32_e32 v4, v0, v4, vcc
	v_lshlrev_b32_e32 v4, 2, v4
	ds_bpermute_b32 v5, v4, v2
	v_max_f32_e32 v2, v2, v2
	ds_bpermute_b32 v4, v4, v1
	v_max_f32_e32 v1, v1, v1
	s_add_i32 s9, s2, s9
	s_waitcnt lgkmcnt(1)
	v_max_f32_e32 v5, v5, v5
	v_max_f32_e32 v2, v2, v5
	v_xor_b32_e32 v5, 2, v0
	v_cmp_lt_i32_e32 vcc, v5, v3
	s_waitcnt lgkmcnt(0)
	v_max_f32_e32 v4, v4, v4
	v_max_f32_e32 v1, v1, v4
	v_cndmask_b32_e32 v5, v0, v5, vcc
	v_lshlrev_b32_e32 v5, 2, v5
	ds_bpermute_b32 v6, v5, v2
	ds_bpermute_b32 v4, v5, v1
	s_and_b32 s10, s9, -8
	s_ashr_i32 s8, s82, 3
	s_sub_i32 s10, s2, s10
	s_waitcnt lgkmcnt(1)
	v_max_f32_e32 v5, v6, v6
	v_max_f32_e32 v2, v2, v5
	v_xor_b32_e32 v5, 4, v0
	v_cmp_lt_i32_e32 vcc, v5, v3
	s_waitcnt lgkmcnt(0)
	v_max_f32_e32 v4, v4, v4
	v_max_f32_e32 v1, v1, v4
	v_cndmask_b32_e32 v5, v0, v5, vcc
	v_lshlrev_b32_e32 v5, 2, v5
	ds_bpermute_b32 v6, v5, v2
	ds_bpermute_b32 v4, v5, v1
	s_mul_i32 s8, s8, s10
	s_ashr_i32 s9, s9, 3
	s_and_b32 s3, s82, 7
	s_waitcnt lgkmcnt(1)
	v_max_f32_e32 v5, v6, v6
	v_max_f32_e32 v2, v2, v5
	v_xor_b32_e32 v5, 8, v0
	v_cmp_lt_i32_e32 vcc, v5, v3
	s_waitcnt lgkmcnt(0)
	v_max_f32_e32 v4, v4, v4
	v_max_f32_e32 v1, v1, v4
	v_cndmask_b32_e32 v5, v0, v5, vcc
	v_lshlrev_b32_e32 v5, 2, v5
	ds_bpermute_b32 v6, v5, v2
	ds_bpermute_b32 v4, v5, v1
	s_add_i32 s8, s8, s9
	s_cmp_eq_u32 s3, 0
	s_cselect_b32 s3, s8, s2
	s_waitcnt lgkmcnt(1)
	v_max_f32_e32 v5, v6, v6
	v_max_f32_e32 v2, v2, v5
	v_xor_b32_e32 v5, 16, v0
	v_cmp_lt_i32_e32 vcc, v5, v3
	s_waitcnt lgkmcnt(0)
	v_max_f32_e32 v4, v4, v4
	v_max_f32_e32 v1, v1, v4
	v_cndmask_b32_e32 v5, v0, v5, vcc
	v_lshlrev_b32_e32 v5, 2, v5
	ds_bpermute_b32 v6, v5, v2
	ds_bpermute_b32 v4, v5, v1
	s_cmpk_gt_i32 s3, 0x7ff
	s_waitcnt lgkmcnt(1)
	v_max_f32_e32 v5, v6, v6
	v_max_f32_e32 v2, v2, v5
	v_xor_b32_e32 v5, 32, v0
	v_cmp_lt_i32_e32 vcc, v5, v3
	s_waitcnt lgkmcnt(0)
	v_max_f32_e32 v4, v4, v4
	v_max_f32_e32 v1, v1, v4
	v_cndmask_b32_e32 v0, v0, v5, vcc
	v_lshlrev_b32_e32 v0, 2, v0
	ds_bpermute_b32 v3, v0, v2
	ds_bpermute_b32 v0, v0, v1
	s_waitcnt lgkmcnt(1)
	v_max_f32_e32 v3, v3, v3
	v_max_f32_e32 v2, v2, v3
	s_waitcnt lgkmcnt(0)
	v_max_f32_e32 v0, v0, v0
	v_max_f32_e32 v0, v1, v0
	v_mul_f32_e32 v1, 0xc1646ddd, v2
	v_mul_f32_e32 v0, v0, v1
	s_nop 0
	v_readfirstlane_b32 s40, v0
	s_cbranch_scc1 .LBB0_1606
	s_load_dwordx2 s[10:11], s[4:5], 0xf0
	s_load_dwordx2 s[12:13], s[6:7], 0xe8
	v_and_b32_e32 v1, 63, v188
	v_and_b32_e32 v3, 0x3c0, v188
	s_add_i32 s4, 0, 0x18000
	v_cmp_gt_u32_e64 s[6:7], 32, v1
	v_lshl_add_u32 v113, v3, 2, s4
	v_lshlrev_b32_e32 v1, 3, v188
	v_lshlrev_b32_e32 v3, 4, v188
	v_lshlrev_b32_e32 v5, 1, v188
	v_lshrrev_b32_e32 v109, 6, v188
	v_and_b32_e32 v4, 0xc0, v3
	v_and_b32_e32 v5, 32, v5
	v_and_b32_e32 v6, 0x118, v1
	v_or3_b32 v4, v5, v4, v6
	v_lshlrev_b32_e32 v5, 3, v109
	v_bfe_u32 v6, v188, 4, 2
	v_bfe_u32 v9, v188, 2, 3
	s_movk_i32 s5, 0x73
	v_bfe_u32 v2, v188, 5, 1
	v_or_b32_e32 v7, v5, v6
	v_or_b32_e32 v5, v5, v9
	v_lshrrev_b32_e32 v9, 1, v188
	v_lshrrev_b32_e32 v10, 4, v188
	v_and_b32_e32 v108, 31, v188
	v_and_b32_e32 v9, 8, v9
	v_and_b32_e32 v10, 4, v10
	v_lshlrev_b32_e32 v117, 4, v2
	s_nop 0
	v_lshlrev_b32_e32 v10, 8, v108
	v_and_b32_e32 v3, 0xf0, v3
	v_or_b32_e32 v11, 32, v117
	v_bitop3_b32 v147, v11, v10, v3 bitop3:0xde
	v_or_b32_e32 v11, 64, v117
	s_cmp_lg_u32 0, -1
	v_bitop3_b32 v148, v11, v10, v3 bitop3:0xde
	v_or_b32_e32 v11, 0x60, v117
	v_lshlrev_b32_e32 v110, 3, v2
	s_cselect_b32 s4, 0, 0
	v_bitop3_b32 v149, v11, v10, v3 bitop3:0xde
	v_or_b32_e32 v11, 0x80, v117
	v_lshlrev_b32_e32 v118, 13, v2
	v_or_b32_e32 v2, 0xc0, v117
	v_mov_b32_e32 v81, 0
	v_add_u32_e32 v115, s4, v4
	v_and_b32_e32 v9, 32, v188
	v_bitop3_b32 v150, v11, v10, v3 bitop3:0xde
	v_or_b32_e32 v11, 0xa0, v117
	s_addk_i32 s4, 0x4000
	v_bitop3_b32 v154, v2, v10, v3 bitop3:0xde
	v_mov_b32_e32 v2, 0xc2c80000
	v_lshlrev_b32_e32 v80, 8, v7
	v_and_or_b32 v1, v1, 24, v9
	v_bitop3_b32 v146, v117, v10, v3 bitop3:0xde
	v_bitop3_b32 v151, v11, v10, v3 bitop3:0xde
	v_add_u32_e32 v152, s4, v4
	v_cmp_nlt_f32_e64 s[8:9], s40, v2
	s_waitcnt lgkmcnt(0)
	v_lshl_add_u64 v[2:3], s[10:11], 0, v[80:81]
	s_mov_b64 s[4:5], 0x12c00000
	v_lshlrev_b32_e32 v80, 7, v5
	v_lshl_or_b32 v111, v109, 5, v108
	v_and_b32_e32 v8, 15, v188
	v_lshl_add_u64 v[120:121], v[2:3], 0, s[4:5]
	v_lshl_add_u64 v[2:3], s[10:11], 0, v[80:81]
	v_lshlrev_b32_e32 v4, 1, v1
	v_mov_b32_e32 v5, v81
	v_lshlrev_b32_e32 v1, 8, v6
	v_mul_u32_u24_e32 v0, 0x600, v111
	v_bitop3_b32 v9, v6, v188, 15 bitop3:0x78
	v_bitop3_b32 v8, v6, v8, 4 bitop3:0x36
	v_lshrrev_b32_e32 v10, 3, v188
	v_and_b32_e32 v10, 8, v10
	v_xor_b32_e32 v9, v9, v10
	v_xor_b32_e32 v8, v8, v10
	s_add_u32 s42, s10, 0xe800000
	v_lshl_add_u64 v[2:3], v[2:3], 0, v[4:5]
	s_mov_b64 s[4:5], 0x1bc00000
	v_lshl_or_b32 v1, v109, 11, v1
	v_lshlrev_b32_e32 v112, 3, v9
	v_lshlrev_b32_e32 v114, 3, v8
	s_movk_i32 s41, 0x4000
	v_lshl_add_u32 v153, v108, 2, v113
	v_lshlrev_b32_e32 v116, 15, v109
	v_mov_b32_e32 v119, v81
	s_addc_u32 s43, s11, 0
	v_lshl_add_u64 v[122:123], v[2:3], 0, s[4:5]
	v_lshl_or_b32 v124, v9, 4, v1
	v_mov_b32_e32 v125, v81
	v_lshl_or_b32 v126, v8, 4, v1
	v_mov_b32_e32 v127, v81
	v_or_b32_e32 v128, v80, v4
	v_mov_b32_e32 v129, v81
	v_lshlrev_b32_e32 v130, 1, v0
	v_lshlrev_b32_e32 v132, 1, v110
	v_mov_b32_e32 v155, 0x358637bd
	s_mov_b32 s44, 0x800000
	s_mov_b64 s[14:15], 0x400
	s_mov_b32 s45, 0xc000
	s_mov_b64 s[16:17], 0x4000
	s_mov_b64 s[18:19], 0x4400
	s_mov_b64 s[20:21], 0x2000
	s_mov_b64 s[22:23], 0x12c08000
	s_mov_b64 s[24:25], 0x12c08400
	s_mov_b64 s[26:27], 0x1bc04000
	s_mov_b64 s[28:29], 0x12c0c000
	s_mov_b64 s[30:31], 0x12c0c400
	s_mov_b64 s[34:35], 0x1bc06000
	s_mov_b64 s[36:37], 0x8000
	s_movk_i32 s47, 0x1000
	s_movk_i32 s48, 0x5000
	s_mov_b32 s49, 0x8000
	s_mov_b32 s54, 0x9000
	s_mov_b32 s55, 0xd000
	s_branch .LBB0_1591

; template <bool SHIFT> __device__ __forceinline__ void attn_dense_body(const bf16* __restrict__ Qb, const bf16* __restrict__ Kh, const bf16* __restrict__ Vh, bf16* __restrict__ Ob, int seq, char* lds, LAS unsigned char* ldsl, float negB, const float* __restrict__ gq, int qpos0) {
;     ...
;   float l_reg = 0; f32x16 o[2] = {}; bf16x8 qr[7];
;     ...
;   f32x16 pA0, pA1, pB0, pB1; bf16x8 pa0, pa1, pa2, pa3; const int NT = seq / KVBLK;
;   DMA(0, 0); asm volatile("s_waitcnt vmcnt(0)" ::: "memory"); __syncthreads();
;   DMA(1, KVBLK);
;   qkt<SHIFT ? 7 : 6>(pA0, pA1, K_lds, qr, r32, hi); partialSM(pA0);
;   asm volatile("s_waitcnt vmcnt(0)" ::: "memory"); __syncthreads();
;   int bv = 0, bk = 1, bw = 2;
.LBB0_1594:
	s_or_b64 exec, exec, s[4:5]
	v_readfirstlane_b32 s60, v109
	s_add_u32 s56, s10, s50
	s_addc_u32 s57, s11, s51
	s_lshl_b32 s60, s60, 11
	s_add_u32 s56, s56, 0x12c00000
	s_addc_u32 s57, s57, 0
	s_add_u32 s58, s10, s52
	s_addc_u32 s59, s11, s53
	s_add_u32 s58, s58, 0x1bc00000
	s_addc_u32 s59, s59, 0
	v_add_u32_e32 v134, 0xc000, v115
	s_add_i32 m0, s60, 0x0
	s_nop 0
	global_load_lds_dwordx4 v124, s[56:57]
	global_load_lds_dwordx4 v126, s[56:57] offset:1024
	s_add_u32 s56, s56, 0x4000
	s_addc_u32 s57, s57, 0
	s_add_i32 m0, s60, 0x4000
	s_nop 0
	global_load_lds_dwordx4 v124, s[56:57]
	global_load_lds_dwordx4 v126, s[56:57] offset:1024
	s_add_u32 s56, s56, 0x4000
	s_addc_u32 s57, s57, 0
	s_add_i32 m0, s60, 0xc000
	s_nop 0
	global_load_lds_dwordx4 v128, s[58:59]
	s_add_u32 s58, s58, 0x2000
	s_addc_u32 s59, s59, 0
	s_add_i32 m0, s60, 0x8000
	s_nop 0
	global_load_lds_dwordx4 v124, s[56:57]
	global_load_lds_dwordx4 v126, s[56:57] offset:1024
	s_add_u32 s56, s56, 0x4000
	s_addc_u32 s57, s57, 0
	s_add_i32 m0, s60, 0x10000
	s_nop 0
	global_load_lds_dwordx4 v128, s[58:59]
	s_add_u32 s58, s58, 0x2000
	s_addc_u32 s59, s59, 0
	v_mov_b32_e32 v0, 0
	v_mov_b32_e32 v1, 0
	v_mov_b32_e32 v2, 0
	v_mov_b32_e32 v3, 0
	v_mov_b32_e32 v4, 0
	v_mov_b32_e32 v5, 0
	v_mov_b32_e32 v6, 0
	v_mov_b32_e32 v7, 0
	v_mov_b32_e32 v8, 0
	v_mov_b32_e32 v9, 0
	v_mov_b32_e32 v10, 0
	v_mov_b32_e32 v11, 0
	v_mov_b32_e32 v12, 0
	v_mov_b32_e32 v13, 0
	v_mov_b32_e32 v14, 0
	v_mov_b32_e32 v15, 0
	v_mov_b32_e32 v16, 0
	v_mov_b32_e32 v17, 0
	v_mov_b32_e32 v18, 0
	v_mov_b32_e32 v19, 0
	v_mov_b32_e32 v20, 0
	v_mov_b32_e32 v21, 0
	v_mov_b32_e32 v22, 0
	v_mov_b32_e32 v23, 0
	v_mov_b32_e32 v24, 0
	v_mov_b32_e32 v25, 0
	v_mov_b32_e32 v26, 0
	v_mov_b32_e32 v27, 0
	v_mov_b32_e32 v28, 0
	v_mov_b32_e32 v29, 0
	v_mov_b32_e32 v30, 0
	v_mov_b32_e32 v31, 0
	v_mov_b32_e32 v133, 0
	v_mov_b32_e32 v135, 0
	s_waitcnt vmcnt(6)
	s_barrier
	ds_read_b128 v[156:159], v146 offset:0
	ds_read_b128 v[160:163], v146 offset:8192
	ds_read_b128 v[164:167], v147 offset:0
	ds_read_b128 v[168:171], v147 offset:8192
	ds_read_b128 v[172:175], v148 offset:0
	ds_read_b128 v[176:179], v148 offset:8192
	ds_read_b128 v[180:183], v149 offset:0
	ds_read_b128 v[184:187], v149 offset:8192
	ds_read_b128 v[64:67], v150 offset:0
	ds_read_b128 v[68:71], v150 offset:8192
	ds_read_b128 v[72:75], v151 offset:0
	ds_read_b128 v[76:79], v151 offset:8192
	s_waitcnt lgkmcnt(0)
	v_mfma_f32_32x32x16_bf16 v[32:47], v[156:159], v[86:89], 0
	v_mfma_f32_32x32x16_bf16 v[48:63], v[160:163], v[86:89], 0
	v_mfma_f32_32x32x16_bf16 v[32:47], v[164:167], v[82:85], v[32:47]
	v_mfma_f32_32x32x16_bf16 v[48:63], v[168:171], v[82:85], v[48:63]
	v_mfma_f32_32x32x16_bf16 v[32:47], v[172:175], v[90:93], v[32:47]
	v_mfma_f32_32x32x16_bf16 v[48:63], v[176:179], v[90:93], v[48:63]
	v_mfma_f32_32x32x16_bf16 v[32:47], v[180:183], v[94:97], v[32:47]
	v_mfma_f32_32x32x16_bf16 v[48:63], v[184:187], v[94:97], v[48:63]
	v_mfma_f32_32x32x16_bf16 v[32:47], v[64:67], v[98:101], v[32:47]
	v_mfma_f32_32x32x16_bf16 v[48:63], v[68:71], v[98:101], v[48:63]
	v_mfma_f32_32x32x16_bf16 v[32:47], v[72:75], v[102:105], v[32:47]
	v_mfma_f32_32x32x16_bf16 v[48:63], v[76:79], v[102:105], v[48:63]
	s_waitcnt lgkmcnt(0)
	s_waitcnt vmcnt(3)
	s_barrier
	ds_read_b128 v[156:159], v146 offset:16384
	ds_read_b128 v[160:163], v146 offset:24576
	ds_read_b128 v[164:167], v147 offset:16384
	ds_read_b128 v[168:171], v147 offset:24576
	ds_read_b128 v[172:175], v148 offset:16384
	ds_read_b128 v[176:179], v148 offset:24576
	ds_read_b128 v[180:183], v149 offset:16384
	ds_read_b128 v[184:187], v149 offset:24576
	ds_read_b128 v[64:67], v150 offset:16384
	ds_read_b128 v[68:71], v150 offset:24576
	ds_read_b128 v[72:75], v151 offset:16384
	ds_read_b128 v[76:79], v151 offset:24576
	v_exp_f32_e32 v32, v32
	v_exp_f32_e32 v33, v33
	v_exp_f32_e32 v34, v34
	v_exp_f32_e32 v35, v35
	v_exp_f32_e32 v36, v36
	v_exp_f32_e32 v37, v37
	v_exp_f32_e32 v38, v38
	v_exp_f32_e32 v39, v39
	v_exp_f32_e32 v40, v40
	v_exp_f32_e32 v41, v41
	v_exp_f32_e32 v42, v42
	v_exp_f32_e32 v43, v43
	v_exp_f32_e32 v44, v44
	v_exp_f32_e32 v45, v45
	v_exp_f32_e32 v46, v46
	v_exp_f32_e32 v47, v47
	s_add_i32 m0, s60, 0x0
	s_nop 0
	global_load_lds_dwordx4 v124, s[56:57]
	global_load_lds_dwordx4 v126, s[56:57] offset:1024
	s_add_u32 s56, s56, 0x4000
	s_addc_u32 s57, s57, 0
	s_add_i32 m0, s60, 0x14000
	s_nop 0
	global_load_lds_dwordx4 v128, s[58:59]
	s_add_u32 s58, s58, 0x2000
	s_addc_u32 s59, s59, 0
	s_mov_b32 s33, 10
; #define SBAR() __builtin_amdgcn_sched_barrier(0)
; #define ROT() do { const int t_ = bv; bv = bk; bk = bw; bw = t_; } while (0)
; __device__ __forceinline__ void partialSM(f32x16& p0) {
; #pragma unroll
;   for (int r = 0; r < 16; ++r) p0[r] = __builtin_amdgcn_exp2f(p0[r]);
; }
; __device__ __forceinline__ void finishSM(f32x16& p0, f32x16& p1, float& l_reg, bf16x8& pa0, bf16x8& pa1, bf16x8& pa2, bf16x8& pa3) {
; #pragma unroll
;   for (int r = 0; r < 16; ++r) p1[r] = __builtin_amdgcn_exp2f(p1[r]);
;   float ps = 0;
; #pragma unroll
;   for (int r = 0; r < 16; ++r) ps += p0[r];
; #pragma unroll
;   for (int r = 0; r < 16; ++r) ps += p1[r];
;   l_reg += ps;
;     ...
;   PK4(p0, 0, pa0); PK4(p0, 8, pa1); PK4(p1, 0, pa2); PK4(p1, 8, pa3);
;     ...
; }
; template <int ND> __device__ __forceinline__ void qkt(f32x16& p0, f32x16& p1, const bf16* Ks, const bf16x8* qr, int r32, int hi) {
;   p0 = f32x16{}; p1 = f32x16{};
; #pragma unroll
;   for (int d0 = 0; d0 < ND; ++d0) { int cb = (d0 * 16 + hi * 8) * 2;
;     bf16x8 b0 = *reinterpret_cast<const bf16x8*>((const char*)Ks + KSWZ(r32, cb));
;     bf16x8 b1 = *reinterpret_cast<const bf16x8*>((const char*)Ks + KSWZ(32 + r32, cb));
;     p0 = __builtin_amdgcn_mfma_f32_32x32x16_bf16(b0, qr[d0], p0, 0, 0, 0);
;     p1 = __builtin_amdgcn_mfma_f32_32x32x16_bf16(b1, qr[d0], p1, 0, 0, 0); }
; }
; template <bool SHIFT> __device__ __forceinline__ void attn_dense_body(const bf16* __restrict__ Qb, const bf16* __restrict__ Kh, const bf16* __restrict__ Vh, bf16* __restrict__ Ob, int seq, char* lds, LAS unsigned char* ldsl, float negB, const float* __restrict__ gq, int qpos0) {
;     ...
;   for (int j = 1; j + 1 < NT; j += 2) {
;     DMA(bw, (j + 1) * KVBLK);
;     SBAR(); qkt<SHIFT ? 7 : 6>(pB0, pB1, (bf16*)((char*)K_lds + bk * SHM_K), qr, r32, hi);
;     finishSM(pA0, pA1, l_reg, pa0, pa1, pa2, pa3); SBAR();
;     pv_d0(o, vb0 + bv * (int)SHM_V, pa0, pa1, pa2, pa3); partialSM(pB0);
;     asm volatile("s_waitcnt vmcnt(0)" ::: "memory"); __syncthreads(); ROT();
;     DMA(bw, (j + 2) * KVBLK);
;     SBAR(); qkt<SHIFT ? 7 : 6>(pA0, pA1, (bf16*)((char*)K_lds + bk * SHM_K), qr, r32, hi);
;     finishSM(pB0, pB1, l_reg, pa0, pa1, pa2, pa3); SBAR();
;     pv_d0(o, vb0 + bv * (int)SHM_V, pa0, pa1, pa2, pa3); partialSM(pA0);
;     asm volatile("s_waitcnt vmcnt(0)" ::: "memory"); __syncthreads(); ROT();
;   }
.Latt_loop:
	s_waitcnt lgkmcnt(0)
	ds_read_b64_tr_b16 v[222:223], v134 offset:0
	ds_read_b64_tr_b16 v[224:225], v134 offset:2048
	ds_read_b64_tr_b16 v[226:227], v134 offset:4096
	ds_read_b64_tr_b16 v[228:229], v134 offset:6144
	ds_read_b64_tr_b16 v[230:231], v134 offset:8192
	ds_read_b64_tr_b16 v[232:233], v134 offset:10240
	ds_read_b64_tr_b16 v[234:235], v134 offset:12288
	ds_read_b64_tr_b16 v[236:237], v134 offset:14336
	v_mfma_f32_32x32x16_bf16 v[190:205], v[156:159], v[86:89], 0
	v_exp_f32_e32 v48, v48
	v_add_f32_e32 v133, v133, v32
	v_exp_f32_e32 v49, v49
	v_add_f32_e32 v135, v135, v33
	v_exp_f32_e32 v50, v50
	v_mfma_f32_32x32x16_bf16 v[206:221], v[160:163], v[86:89], 0
	v_add_f32_e32 v133, v133, v34
	v_exp_f32_e32 v51, v51
	v_add_f32_e32 v135, v135, v35
	v_exp_f32_e32 v52, v52
	v_add_f32_e32 v133, v133, v36
	v_mfma_f32_32x32x16_bf16 v[190:205], v[164:167], v[82:85], v[190:205]
	v_exp_f32_e32 v53, v53
	v_add_f32_e32 v135, v135, v37
	v_exp_f32_e32 v54, v54
	v_add_f32_e32 v133, v133, v38
	v_exp_f32_e32 v55, v55
	v_add_f32_e32 v135, v135, v39
	v_mfma_f32_32x32x16_bf16 v[206:221], v[168:171], v[82:85], v[206:221]
	s_waitcnt lgkmcnt(7)
	ds_read_b64_tr_b16 v[238:239], v134 offset:512
	ds_read_b64_tr_b16 v[240:241], v134 offset:2560
	ds_read_b64_tr_b16 v[242:243], v134 offset:4608
	ds_read_b64_tr_b16 v[244:245], v134 offset:6656
	ds_read_b64_tr_b16 v[246:247], v134 offset:8704
	ds_read_b64_tr_b16 v[248:249], v134 offset:10752
	ds_read_b64_tr_b16 v[140:141], v134 offset:12800
	ds_read_b64_tr_b16 v[142:143], v134 offset:14848
	v_exp_f32_e32 v56, v56
	v_add_f32_e32 v133, v133, v40
	v_exp_f32_e32 v57, v57
	v_add_f32_e32 v135, v135, v41
	v_exp_f32_e32 v58, v58
	v_mfma_f32_32x32x16_bf16 v[190:205], v[172:175], v[90:93], v[190:205]
	v_add_f32_e32 v133, v133, v42
	v_exp_f32_e32 v59, v59
	v_add_f32_e32 v135, v135, v43
	v_exp_f32_e32 v60, v60
	v_add_f32_e32 v133, v133, v44
	v_mfma_f32_32x32x16_bf16 v[206:221], v[176:179], v[90:93], v[206:221]
	v_exp_f32_e32 v61, v61
	v_add_f32_e32 v135, v135, v45
	v_exp_f32_e32 v62, v62
	v_add_f32_e32 v133, v133, v46
	v_exp_f32_e32 v63, v63
	v_add_f32_e32 v135, v135, v47
	v_mfma_f32_32x32x16_bf16 v[190:205], v[180:183], v[94:97], v[190:205]
	v_add_f32_e32 v133, v133, v48
	v_add_f32_e32 v135, v135, v49
	v_add_f32_e32 v133, v133, v50
	v_add_f32_e32 v135, v135, v51
	v_add_f32_e32 v133, v133, v52
	v_mfma_f32_32x32x16_bf16 v[206:221], v[184:187], v[94:97], v[206:221]
	v_add_f32_e32 v135, v135, v53
	v_add_f32_e32 v133, v133, v54
	v_add_f32_e32 v135, v135, v55
	v_add_f32_e32 v133, v133, v56
	v_add_f32_e32 v135, v135, v57
	v_mfma_f32_32x32x16_bf16 v[190:205], v[64:67], v[98:101], v[190:205]
	v_add_f32_e32 v133, v133, v58
	v_add_f32_e32 v135, v135, v59
	v_add_f32_e32 v133, v133, v60
	v_add_f32_e32 v135, v135, v61
	v_add_f32_e32 v133, v133, v62
	v_add_f32_e32 v135, v135, v63
	v_mfma_f32_32x32x16_bf16 v[206:221], v[68:71], v[98:101], v[206:221]
	v_cvt_pk_bf16_f32 v32, v32, v33
	v_cvt_pk_bf16_f32 v33, v34, v35
	v_cvt_pk_bf16_f32 v34, v36, v37
	v_cvt_pk_bf16_f32 v35, v38, v39
	v_cvt_pk_bf16_f32 v36, v40, v41
	v_mfma_f32_32x32x16_bf16 v[190:205], v[72:75], v[102:105], v[190:205]
	v_cvt_pk_bf16_f32 v37, v42, v43
	v_cvt_pk_bf16_f32 v38, v44, v45
	v_cvt_pk_bf16_f32 v39, v46, v47
	v_cvt_pk_bf16_f32 v48, v48, v49
	v_cvt_pk_bf16_f32 v49, v50, v51
	v_mfma_f32_32x32x16_bf16 v[206:221], v[76:79], v[102:105], v[206:221]
	v_cvt_pk_bf16_f32 v50, v52, v53
	v_cvt_pk_bf16_f32 v51, v54, v55
	v_cvt_pk_bf16_f32 v52, v56, v57
	v_cvt_pk_bf16_f32 v53, v58, v59
	v_cvt_pk_bf16_f32 v54, v60, v61
	v_cvt_pk_bf16_f32 v55, v62, v63
	s_waitcnt lgkmcnt(0)
	s_waitcnt vmcnt(3)
	s_barrier
	ds_read_b128 v[156:159], v146 offset:32768
	ds_read_b128 v[160:163], v146 offset:40960
	ds_read_b128 v[164:167], v147 offset:32768
	ds_read_b128 v[168:171], v147 offset:40960
	ds_read_b128 v[172:175], v148 offset:32768
	ds_read_b128 v[176:179], v148 offset:40960
	ds_read_b128 v[180:183], v149 offset:32768
	ds_read_b128 v[184:187], v149 offset:40960
	ds_read_b128 v[64:67], v150 offset:32768
	ds_read_b128 v[68:71], v150 offset:40960
	ds_read_b128 v[72:75], v151 offset:32768
	ds_read_b128 v[76:79], v151 offset:40960
	v_mfma_f32_32x32x16_bf16 v[0:15], v[32:35], v[222:225], v[0:15]
	s_add_i32 m0, s60, 0x4000
	v_exp_f32_e32 v190, v190
	v_exp_f32_e32 v191, v191
	v_mfma_f32_32x32x16_bf16 v[0:15], v[36:39], v[226:229], v[0:15]
	global_load_lds_dwordx4 v124, s[56:57]
	global_load_lds_dwordx4 v126, s[56:57] offset:1024
	v_exp_f32_e32 v192, v192
	v_exp_f32_e32 v193, v193
	v_mfma_f32_32x32x16_bf16 v[0:15], v[48:51], v[230:233], v[0:15]
	s_add_u32 s56, s56, 0x4000
	s_addc_u32 s57, s57, 0
	v_exp_f32_e32 v194, v194
	v_exp_f32_e32 v195, v195
	v_mfma_f32_32x32x16_bf16 v[0:15], v[52:55], v[234:237], v[0:15]
	s_add_i32 m0, s60, 0xc000
	v_exp_f32_e32 v196, v196
	v_exp_f32_e32 v197, v197
	v_mfma_f32_32x32x16_bf16 v[16:31], v[32:35], v[238:241], v[16:31]
	global_load_lds_dwordx4 v128, s[58:59]
	v_exp_f32_e32 v198, v198
	v_exp_f32_e32 v199, v199
	v_mfma_f32_32x32x16_bf16 v[16:31], v[36:39], v[242:245], v[16:31]
	s_add_u32 s58, s58, 0x2000
	s_addc_u32 s59, s59, 0
	v_exp_f32_e32 v200, v200
	v_exp_f32_e32 v201, v201
	v_mfma_f32_32x32x16_bf16 v[16:31], v[48:51], v[246:249], v[16:31]
	v_exp_f32_e32 v202, v202
	v_exp_f32_e32 v203, v203
	v_mfma_f32_32x32x16_bf16 v[16:31], v[52:55], v[140:143], v[16:31]
	v_exp_f32_e32 v204, v204
	v_exp_f32_e32 v205, v205
	s_waitcnt lgkmcnt(0)
; #define SBAR() __builtin_amdgcn_sched_barrier(0)
; #define ROT() do { const int t_ = bv; bv = bk; bk = bw; bw = t_; } while (0)
; __device__ __forceinline__ void partialSM(f32x16& p0) {
; #pragma unroll
;   for (int r = 0; r < 16; ++r) p0[r] = __builtin_amdgcn_exp2f(p0[r]);
; }
; __device__ __forceinline__ void finishSM(f32x16& p0, f32x16& p1, float& l_reg, bf16x8& pa0, bf16x8& pa1, bf16x8& pa2, bf16x8& pa3) {
; #pragma unroll
;   for (int r = 0; r < 16; ++r) p1[r] = __builtin_amdgcn_exp2f(p1[r]);
;   float ps = 0;
; #pragma unroll
;   for (int r = 0; r < 16; ++r) ps += p0[r];
; #pragma unroll
;   for (int r = 0; r < 16; ++r) ps += p1[r];
;   l_reg += ps;
;     ...
;   PK4(p0, 0, pa0); PK4(p0, 8, pa1); PK4(p1, 0, pa2); PK4(p1, 8, pa3);
;     ...
; }
; template <int ND> __device__ __forceinline__ void qkt(f32x16& p0, f32x16& p1, const bf16* Ks, const bf16x8* qr, int r32, int hi) {
;   p0 = f32x16{}; p1 = f32x16{};
; #pragma unroll
;   for (int d0 = 0; d0 < ND; ++d0) { int cb = (d0 * 16 + hi * 8) * 2;
;     bf16x8 b0 = *reinterpret_cast<const bf16x8*>((const char*)Ks + KSWZ(r32, cb));
;     bf16x8 b1 = *reinterpret_cast<const bf16x8*>((const char*)Ks + KSWZ(32 + r32, cb));
;     p0 = __builtin_amdgcn_mfma_f32_32x32x16_bf16(b0, qr[d0], p0, 0, 0, 0);
;     p1 = __builtin_amdgcn_mfma_f32_32x32x16_bf16(b1, qr[d0], p1, 0, 0, 0); }
; }
; template <bool SHIFT> __device__ __forceinline__ void attn_dense_body(const bf16* __restrict__ Qb, const bf16* __restrict__ Kh, const bf16* __restrict__ Vh, bf16* __restrict__ Ob, int seq, char* lds, LAS unsigned char* ldsl, float negB, const float* __restrict__ gq, int qpos0) {
;     ...
;   for (int j = 1; j + 1 < NT; j += 2) {
;     DMA(bw, (j + 1) * KVBLK);
;     SBAR(); qkt<SHIFT ? 7 : 6>(pB0, pB1, (bf16*)((char*)K_lds + bk * SHM_K), qr, r32, hi);
;     finishSM(pA0, pA1, l_reg, pa0, pa1, pa2, pa3); SBAR();
;     pv_d0(o, vb0 + bv * (int)SHM_V, pa0, pa1, pa2, pa3); partialSM(pB0);
;     asm volatile("s_waitcnt vmcnt(0)" ::: "memory"); __syncthreads(); ROT();
;     DMA(bw, (j + 2) * KVBLK);
;     SBAR(); qkt<SHIFT ? 7 : 6>(pA0, pA1, (bf16*)((char*)K_lds + bk * SHM_K), qr, r32, hi);
;     finishSM(pB0, pB1, l_reg, pa0, pa1, pa2, pa3); SBAR();
;     pv_d0(o, vb0 + bv * (int)SHM_V, pa0, pa1, pa2, pa3); partialSM(pA0);
;     asm volatile("s_waitcnt vmcnt(0)" ::: "memory"); __syncthreads(); ROT();
;   }
	ds_read_b64_tr_b16 v[222:223], v134 offset:16384
	ds_read_b64_tr_b16 v[224:225], v134 offset:18432
	ds_read_b64_tr_b16 v[226:227], v134 offset:20480
	ds_read_b64_tr_b16 v[228:229], v134 offset:22528
	ds_read_b64_tr_b16 v[230:231], v134 offset:24576
	ds_read_b64_tr_b16 v[232:233], v134 offset:26624
	ds_read_b64_tr_b16 v[234:235], v134 offset:28672
	ds_read_b64_tr_b16 v[236:237], v134 offset:30720
	v_mfma_f32_32x32x16_bf16 v[32:47], v[156:159], v[86:89], 0
	v_exp_f32_e32 v206, v206
	v_add_f32_e32 v133, v133, v190
	v_exp_f32_e32 v207, v207
	v_add_f32_e32 v135, v135, v191
	v_exp_f32_e32 v208, v208
	v_mfma_f32_32x32x16_bf16 v[48:63], v[160:163], v[86:89], 0
	v_add_f32_e32 v133, v133, v192
	v_exp_f32_e32 v209, v209
	v_add_f32_e32 v135, v135, v193
	v_exp_f32_e32 v210, v210
	v_add_f32_e32 v133, v133, v194
	v_mfma_f32_32x32x16_bf16 v[32:47], v[164:167], v[82:85], v[32:47]
	v_exp_f32_e32 v211, v211
	v_add_f32_e32 v135, v135, v195
	v_exp_f32_e32 v212, v212
	v_add_f32_e32 v133, v133, v196
	v_exp_f32_e32 v213, v213
	v_add_f32_e32 v135, v135, v197
	v_mfma_f32_32x32x16_bf16 v[48:63], v[168:171], v[82:85], v[48:63]
	s_waitcnt lgkmcnt(7)
	ds_read_b64_tr_b16 v[238:239], v134 offset:16896
	ds_read_b64_tr_b16 v[240:241], v134 offset:18944
	ds_read_b64_tr_b16 v[242:243], v134 offset:20992
	ds_read_b64_tr_b16 v[244:245], v134 offset:23040
	ds_read_b64_tr_b16 v[246:247], v134 offset:25088
	ds_read_b64_tr_b16 v[248:249], v134 offset:27136
	ds_read_b64_tr_b16 v[140:141], v134 offset:29184
	ds_read_b64_tr_b16 v[142:143], v134 offset:31232
	v_exp_f32_e32 v214, v214
	v_add_f32_e32 v133, v133, v198
	v_exp_f32_e32 v215, v215
	v_add_f32_e32 v135, v135, v199
	v_exp_f32_e32 v216, v216
	v_mfma_f32_32x32x16_bf16 v[32:47], v[172:175], v[90:93], v[32:47]
	v_add_f32_e32 v133, v133, v200
	v_exp_f32_e32 v217, v217
	v_add_f32_e32 v135, v135, v201
	v_exp_f32_e32 v218, v218
	v_add_f32_e32 v133, v133, v202
	v_mfma_f32_32x32x16_bf16 v[48:63], v[176:179], v[90:93], v[48:63]
	v_exp_f32_e32 v219, v219
	v_add_f32_e32 v135, v135, v203
	v_exp_f32_e32 v220, v220
	v_add_f32_e32 v133, v133, v204
	v_exp_f32_e32 v221, v221
	v_add_f32_e32 v135, v135, v205
	v_mfma_f32_32x32x16_bf16 v[32:47], v[180:183], v[94:97], v[32:47]
	v_add_f32_e32 v133, v133, v206
	v_add_f32_e32 v135, v135, v207
	v_add_f32_e32 v133, v133, v208
	v_add_f32_e32 v135, v135, v209
	v_add_f32_e32 v133, v133, v210
	v_mfma_f32_32x32x16_bf16 v[48:63], v[184:187], v[94:97], v[48:63]
	v_add_f32_e32 v135, v135, v211
	v_add_f32_e32 v133, v133, v212
	v_add_f32_e32 v135, v135, v213
	v_add_f32_e32 v133, v133, v214
	v_add_f32_e32 v135, v135, v215
	v_mfma_f32_32x32x16_bf16 v[32:47], v[64:67], v[98:101], v[32:47]
	v_add_f32_e32 v133, v133, v216
	v_add_f32_e32 v135, v135, v217
	v_add_f32_e32 v133, v133, v218
	v_add_f32_e32 v135, v135, v219
	v_add_f32_e32 v133, v133, v220
	v_add_f32_e32 v135, v135, v221
	v_mfma_f32_32x32x16_bf16 v[48:63], v[68:71], v[98:101], v[48:63]
	v_cvt_pk_bf16_f32 v190, v190, v191
	v_cvt_pk_bf16_f32 v191, v192, v193
	v_cvt_pk_bf16_f32 v192, v194, v195
	v_cvt_pk_bf16_f32 v193, v196, v197
	v_cvt_pk_bf16_f32 v194, v198, v199
	v_mfma_f32_32x32x16_bf16 v[32:47], v[72:75], v[102:105], v[32:47]
	v_cvt_pk_bf16_f32 v195, v200, v201
	v_cvt_pk_bf16_f32 v196, v202, v203
	v_cvt_pk_bf16_f32 v197, v204, v205
	v_cvt_pk_bf16_f32 v206, v206, v207
	v_cvt_pk_bf16_f32 v207, v208, v209
	v_mfma_f32_32x32x16_bf16 v[48:63], v[76:79], v[102:105], v[48:63]
	v_cvt_pk_bf16_f32 v208, v210, v211
	v_cvt_pk_bf16_f32 v209, v212, v213
	v_cvt_pk_bf16_f32 v210, v214, v215
	v_cvt_pk_bf16_f32 v211, v216, v217
	v_cvt_pk_bf16_f32 v212, v218, v219
	v_cvt_pk_bf16_f32 v213, v220, v221
	s_waitcnt lgkmcnt(0)
	s_waitcnt vmcnt(3)
	s_barrier
	ds_read_b128 v[156:159], v146 offset:0
	ds_read_b128 v[160:163], v146 offset:8192
	ds_read_b128 v[164:167], v147 offset:0
	ds_read_b128 v[168:171], v147 offset:8192
	ds_read_b128 v[172:175], v148 offset:0
	ds_read_b128 v[176:179], v148 offset:8192
	ds_read_b128 v[180:183], v149 offset:0
	ds_read_b128 v[184:187], v149 offset:8192
	ds_read_b128 v[64:67], v150 offset:0
	ds_read_b128 v[68:71], v150 offset:8192
	ds_read_b128 v[72:75], v151 offset:0
	ds_read_b128 v[76:79], v151 offset:8192
	v_mfma_f32_32x32x16_bf16 v[0:15], v[190:193], v[222:225], v[0:15]
	s_add_i32 m0, s60, 0x8000
	v_exp_f32_e32 v32, v32
	v_exp_f32_e32 v33, v33
	v_mfma_f32_32x32x16_bf16 v[0:15], v[194:197], v[226:229], v[0:15]
	global_load_lds_dwordx4 v124, s[56:57]
	global_load_lds_dwordx4 v126, s[56:57] offset:1024
	v_exp_f32_e32 v34, v34
	v_exp_f32_e32 v35, v35
	v_mfma_f32_32x32x16_bf16 v[0:15], v[206:209], v[230:233], v[0:15]
	s_add_u32 s56, s56, 0x4000
	s_addc_u32 s57, s57, 0
	v_exp_f32_e32 v36, v36
	v_exp_f32_e32 v37, v37
	v_mfma_f32_32x32x16_bf16 v[0:15], v[210:213], v[234:237], v[0:15]
	s_add_i32 m0, s60, 0x10000
	v_exp_f32_e32 v38, v38
	v_exp_f32_e32 v39, v39
	v_mfma_f32_32x32x16_bf16 v[16:31], v[190:193], v[238:241], v[16:31]
	global_load_lds_dwordx4 v128, s[58:59]
	v_exp_f32_e32 v40, v40
	v_exp_f32_e32 v41, v41
	v_mfma_f32_32x32x16_bf16 v[16:31], v[194:197], v[242:245], v[16:31]
	s_add_u32 s58, s58, 0x2000
	s_addc_u32 s59, s59, 0
	v_exp_f32_e32 v42, v42
	v_exp_f32_e32 v43, v43
	v_mfma_f32_32x32x16_bf16 v[16:31], v[206:209], v[246:249], v[16:31]
	v_exp_f32_e32 v44, v44
	v_exp_f32_e32 v45, v45
	v_mfma_f32_32x32x16_bf16 v[16:31], v[210:213], v[140:143], v[16:31]
	v_exp_f32_e32 v46, v46
	v_exp_f32_e32 v47, v47
	s_waitcnt lgkmcnt(0)
; #define SBAR() __builtin_amdgcn_sched_barrier(0)
; #define ROT() do { const int t_ = bv; bv = bk; bk = bw; bw = t_; } while (0)
; __device__ __forceinline__ void partialSM(f32x16& p0) {
; #pragma unroll
;   for (int r = 0; r < 16; ++r) p0[r] = __builtin_amdgcn_exp2f(p0[r]);
; }
; __device__ __forceinline__ void finishSM(f32x16& p0, f32x16& p1, float& l_reg, bf16x8& pa0, bf16x8& pa1, bf16x8& pa2, bf16x8& pa3) {
; #pragma unroll
;   for (int r = 0; r < 16; ++r) p1[r] = __builtin_amdgcn_exp2f(p1[r]);
;   float ps = 0;
; #pragma unroll
;   for (int r = 0; r < 16; ++r) ps += p0[r];
; #pragma unroll
;   for (int r = 0; r < 16; ++r) ps += p1[r];
;   l_reg += ps;
;     ...
;   PK4(p0, 0, pa0); PK4(p0, 8, pa1); PK4(p1, 0, pa2); PK4(p1, 8, pa3);
;     ...
; }
; template <int ND> __device__ __forceinline__ void qkt(f32x16& p0, f32x16& p1, const bf16* Ks, const bf16x8* qr, int r32, int hi) {
;   p0 = f32x16{}; p1 = f32x16{};
; #pragma unroll
;   for (int d0 = 0; d0 < ND; ++d0) { int cb = (d0 * 16 + hi * 8) * 2;
;     bf16x8 b0 = *reinterpret_cast<const bf16x8*>((const char*)Ks + KSWZ(r32, cb));
;     bf16x8 b1 = *reinterpret_cast<const bf16x8*>((const char*)Ks + KSWZ(32 + r32, cb));
;     p0 = __builtin_amdgcn_mfma_f32_32x32x16_bf16(b0, qr[d0], p0, 0, 0, 0);
;     p1 = __builtin_amdgcn_mfma_f32_32x32x16_bf16(b1, qr[d0], p1, 0, 0, 0); }
; }
; template <bool SHIFT> __device__ __forceinline__ void attn_dense_body(const bf16* __restrict__ Qb, const bf16* __restrict__ Kh, const bf16* __restrict__ Vh, bf16* __restrict__ Ob, int seq, char* lds, LAS unsigned char* ldsl, float negB, const float* __restrict__ gq, int qpos0) {
;     ...
;   for (int j = 1; j + 1 < NT; j += 2) {
;     DMA(bw, (j + 1) * KVBLK);
;     SBAR(); qkt<SHIFT ? 7 : 6>(pB0, pB1, (bf16*)((char*)K_lds + bk * SHM_K), qr, r32, hi);
;     finishSM(pA0, pA1, l_reg, pa0, pa1, pa2, pa3); SBAR();
;     pv_d0(o, vb0 + bv * (int)SHM_V, pa0, pa1, pa2, pa3); partialSM(pB0);
;     asm volatile("s_waitcnt vmcnt(0)" ::: "memory"); __syncthreads(); ROT();
;     DMA(bw, (j + 2) * KVBLK);
;     SBAR(); qkt<SHIFT ? 7 : 6>(pA0, pA1, (bf16*)((char*)K_lds + bk * SHM_K), qr, r32, hi);
;     finishSM(pB0, pB1, l_reg, pa0, pa1, pa2, pa3); SBAR();
;     pv_d0(o, vb0 + bv * (int)SHM_V, pa0, pa1, pa2, pa3); partialSM(pA0);
;     asm volatile("s_waitcnt vmcnt(0)" ::: "memory"); __syncthreads(); ROT();
;   }
	ds_read_b64_tr_b16 v[222:223], v134 offset:32768
	ds_read_b64_tr_b16 v[224:225], v134 offset:34816
	ds_read_b64_tr_b16 v[226:227], v134 offset:36864
	ds_read_b64_tr_b16 v[228:229], v134 offset:38912
	ds_read_b64_tr_b16 v[230:231], v134 offset:40960
	ds_read_b64_tr_b16 v[232:233], v134 offset:43008
	ds_read_b64_tr_b16 v[234:235], v134 offset:45056
	ds_read_b64_tr_b16 v[236:237], v134 offset:47104
	v_mfma_f32_32x32x16_bf16 v[190:205], v[156:159], v[86:89], 0
	v_exp_f32_e32 v48, v48
	v_add_f32_e32 v133, v133, v32
	v_exp_f32_e32 v49, v49
	v_add_f32_e32 v135, v135, v33
	v_exp_f32_e32 v50, v50
	v_mfma_f32_32x32x16_bf16 v[206:221], v[160:163], v[86:89], 0
	v_add_f32_e32 v133, v133, v34
	v_exp_f32_e32 v51, v51
	v_add_f32_e32 v135, v135, v35
	v_exp_f32_e32 v52, v52
	v_add_f32_e32 v133, v133, v36
	v_mfma_f32_32x32x16_bf16 v[190:205], v[164:167], v[82:85], v[190:205]
	v_exp_f32_e32 v53, v53
	v_add_f32_e32 v135, v135, v37
	v_exp_f32_e32 v54, v54
	v_add_f32_e32 v133, v133, v38
	v_exp_f32_e32 v55, v55
	v_add_f32_e32 v135, v135, v39
	v_mfma_f32_32x32x16_bf16 v[206:221], v[168:171], v[82:85], v[206:221]
	s_waitcnt lgkmcnt(7)
	ds_read_b64_tr_b16 v[238:239], v134 offset:33280
	ds_read_b64_tr_b16 v[240:241], v134 offset:35328
	ds_read_b64_tr_b16 v[242:243], v134 offset:37376
	ds_read_b64_tr_b16 v[244:245], v134 offset:39424
	ds_read_b64_tr_b16 v[246:247], v134 offset:41472
	ds_read_b64_tr_b16 v[248:249], v134 offset:43520
	ds_read_b64_tr_b16 v[140:141], v134 offset:45568
	ds_read_b64_tr_b16 v[142:143], v134 offset:47616
	v_exp_f32_e32 v56, v56
	v_add_f32_e32 v133, v133, v40
	v_exp_f32_e32 v57, v57
	v_add_f32_e32 v135, v135, v41
	v_exp_f32_e32 v58, v58
	v_mfma_f32_32x32x16_bf16 v[190:205], v[172:175], v[90:93], v[190:205]
	v_add_f32_e32 v133, v133, v42
	v_exp_f32_e32 v59, v59
	v_add_f32_e32 v135, v135, v43
	v_exp_f32_e32 v60, v60
	v_add_f32_e32 v133, v133, v44
	v_mfma_f32_32x32x16_bf16 v[206:221], v[176:179], v[90:93], v[206:221]
	v_exp_f32_e32 v61, v61
	v_add_f32_e32 v135, v135, v45
	v_exp_f32_e32 v62, v62
	v_add_f32_e32 v133, v133, v46
	v_exp_f32_e32 v63, v63
	v_add_f32_e32 v135, v135, v47
	v_mfma_f32_32x32x16_bf16 v[190:205], v[180:183], v[94:97], v[190:205]
	v_add_f32_e32 v133, v133, v48
	v_add_f32_e32 v135, v135, v49
	v_add_f32_e32 v133, v133, v50
	v_add_f32_e32 v135, v135, v51
	v_add_f32_e32 v133, v133, v52
	v_mfma_f32_32x32x16_bf16 v[206:221], v[184:187], v[94:97], v[206:221]
	v_add_f32_e32 v135, v135, v53
	v_add_f32_e32 v133, v133, v54
	v_add_f32_e32 v135, v135, v55
	v_add_f32_e32 v133, v133, v56
	v_add_f32_e32 v135, v135, v57
	v_mfma_f32_32x32x16_bf16 v[190:205], v[64:67], v[98:101], v[190:205]
	v_add_f32_e32 v133, v133, v58
	v_add_f32_e32 v135, v135, v59
	v_add_f32_e32 v133, v133, v60
	v_add_f32_e32 v135, v135, v61
	v_add_f32_e32 v133, v133, v62
	v_add_f32_e32 v135, v135, v63
	v_mfma_f32_32x32x16_bf16 v[206:221], v[68:71], v[98:101], v[206:221]
	v_cvt_pk_bf16_f32 v32, v32, v33
	v_cvt_pk_bf16_f32 v33, v34, v35
	v_cvt_pk_bf16_f32 v34, v36, v37
	v_cvt_pk_bf16_f32 v35, v38, v39
	v_cvt_pk_bf16_f32 v36, v40, v41
	v_mfma_f32_32x32x16_bf16 v[190:205], v[72:75], v[102:105], v[190:205]
	v_cvt_pk_bf16_f32 v37, v42, v43
	v_cvt_pk_bf16_f32 v38, v44, v45
	v_cvt_pk_bf16_f32 v39, v46, v47
	v_cvt_pk_bf16_f32 v48, v48, v49
	v_cvt_pk_bf16_f32 v49, v50, v51
	v_mfma_f32_32x32x16_bf16 v[206:221], v[76:79], v[102:105], v[206:221]
	v_cvt_pk_bf16_f32 v50, v52, v53
	v_cvt_pk_bf16_f32 v51, v54, v55
	v_cvt_pk_bf16_f32 v52, v56, v57
	v_cvt_pk_bf16_f32 v53, v58, v59
	v_cvt_pk_bf16_f32 v54, v60, v61
	v_cvt_pk_bf16_f32 v55, v62, v63
	s_waitcnt lgkmcnt(0)
	s_waitcnt vmcnt(3)
	s_barrier
	ds_read_b128 v[156:159], v146 offset:16384
	ds_read_b128 v[160:163], v146 offset:24576
	ds_read_b128 v[164:167], v147 offset:16384
	ds_read_b128 v[168:171], v147 offset:24576
	ds_read_b128 v[172:175], v148 offset:16384
	ds_read_b128 v[176:179], v148 offset:24576
	ds_read_b128 v[180:183], v149 offset:16384
	ds_read_b128 v[184:187], v149 offset:24576
	ds_read_b128 v[64:67], v150 offset:16384
	ds_read_b128 v[68:71], v150 offset:24576
	ds_read_b128 v[72:75], v151 offset:16384
	ds_read_b128 v[76:79], v151 offset:24576
	v_mfma_f32_32x32x16_bf16 v[0:15], v[32:35], v[222:225], v[0:15]
	s_add_i32 m0, s60, 0x0
	v_exp_f32_e32 v190, v190
	v_exp_f32_e32 v191, v191
	v_mfma_f32_32x32x16_bf16 v[0:15], v[36:39], v[226:229], v[0:15]
	global_load_lds_dwordx4 v124, s[56:57]
	global_load_lds_dwordx4 v126, s[56:57] offset:1024
	v_exp_f32_e32 v192, v192
	v_exp_f32_e32 v193, v193
	v_mfma_f32_32x32x16_bf16 v[0:15], v[48:51], v[230:233], v[0:15]
	s_add_u32 s56, s56, 0x4000
	s_addc_u32 s57, s57, 0
	v_exp_f32_e32 v194, v194
	v_exp_f32_e32 v195, v195
	v_mfma_f32_32x32x16_bf16 v[0:15], v[52:55], v[234:237], v[0:15]
	s_add_i32 m0, s60, 0x14000
	v_exp_f32_e32 v196, v196
	v_exp_f32_e32 v197, v197
	v_mfma_f32_32x32x16_bf16 v[16:31], v[32:35], v[238:241], v[16:31]
	global_load_lds_dwordx4 v128, s[58:59]
	v_exp_f32_e32 v198, v198
	v_exp_f32_e32 v199, v199
	v_mfma_f32_32x32x16_bf16 v[16:31], v[36:39], v[242:245], v[16:31]
	s_add_u32 s58, s58, 0x2000
	s_addc_u32 s59, s59, 0
	v_exp_f32_e32 v200, v200
	v_exp_f32_e32 v201, v201
	v_mfma_f32_32x32x16_bf16 v[16:31], v[48:51], v[246:249], v[16:31]
	v_exp_f32_e32 v202, v202
	v_exp_f32_e32 v203, v203
	v_mfma_f32_32x32x16_bf16 v[16:31], v[52:55], v[140:143], v[16:31]
	v_exp_f32_e32 v204, v204
	v_exp_f32_e32 v205, v205
	s_waitcnt lgkmcnt(0)
; #define SBAR() __builtin_amdgcn_sched_barrier(0)
; #define ROT() do { const int t_ = bv; bv = bk; bk = bw; bw = t_; } while (0)
; __device__ __forceinline__ void partialSM(f32x16& p0) {
; #pragma unroll
;   for (int r = 0; r < 16; ++r) p0[r] = __builtin_amdgcn_exp2f(p0[r]);
; }
; __device__ __forceinline__ void finishSM(f32x16& p0, f32x16& p1, float& l_reg, bf16x8& pa0, bf16x8& pa1, bf16x8& pa2, bf16x8& pa3) {
; #pragma unroll
;   for (int r = 0; r < 16; ++r) p1[r] = __builtin_amdgcn_exp2f(p1[r]);
;   float ps = 0;
; #pragma unroll
;   for (int r = 0; r < 16; ++r) ps += p0[r];
; #pragma unroll
;   for (int r = 0; r < 16; ++r) ps += p1[r];
;   l_reg += ps;
;     ...
;   PK4(p0, 0, pa0); PK4(p0, 8, pa1); PK4(p1, 0, pa2); PK4(p1, 8, pa3);
;     ...
; }
; template <int ND> __device__ __forceinline__ void qkt(f32x16& p0, f32x16& p1, const bf16* Ks, const bf16x8* qr, int r32, int hi) {
;   p0 = f32x16{}; p1 = f32x16{};
; #pragma unroll
;   for (int d0 = 0; d0 < ND; ++d0) { int cb = (d0 * 16 + hi * 8) * 2;
;     bf16x8 b0 = *reinterpret_cast<const bf16x8*>((const char*)Ks + KSWZ(r32, cb));
;     bf16x8 b1 = *reinterpret_cast<const bf16x8*>((const char*)Ks + KSWZ(32 + r32, cb));
;     p0 = __builtin_amdgcn_mfma_f32_32x32x16_bf16(b0, qr[d0], p0, 0, 0, 0);
;     p1 = __builtin_amdgcn_mfma_f32_32x32x16_bf16(b1, qr[d0], p1, 0, 0, 0); }
; }
; template <bool SHIFT> __device__ __forceinline__ void attn_dense_body(const bf16* __restrict__ Qb, const bf16* __restrict__ Kh, const bf16* __restrict__ Vh, bf16* __restrict__ Ob, int seq, char* lds, LAS unsigned char* ldsl, float negB, const float* __restrict__ gq, int qpos0) {
;     ...
;   for (int j = 1; j + 1 < NT; j += 2) {
;     DMA(bw, (j + 1) * KVBLK);
;     SBAR(); qkt<SHIFT ? 7 : 6>(pB0, pB1, (bf16*)((char*)K_lds + bk * SHM_K), qr, r32, hi);
;     finishSM(pA0, pA1, l_reg, pa0, pa1, pa2, pa3); SBAR();
;     pv_d0(o, vb0 + bv * (int)SHM_V, pa0, pa1, pa2, pa3); partialSM(pB0);
;     asm volatile("s_waitcnt vmcnt(0)" ::: "memory"); __syncthreads(); ROT();
;     DMA(bw, (j + 2) * KVBLK);
;     SBAR(); qkt<SHIFT ? 7 : 6>(pA0, pA1, (bf16*)((char*)K_lds + bk * SHM_K), qr, r32, hi);
;     finishSM(pB0, pB1, l_reg, pa0, pa1, pa2, pa3); SBAR();
;     pv_d0(o, vb0 + bv * (int)SHM_V, pa0, pa1, pa2, pa3); partialSM(pA0);
;     asm volatile("s_waitcnt vmcnt(0)" ::: "memory"); __syncthreads(); ROT();
;   }
	ds_read_b64_tr_b16 v[222:223], v134 offset:0
	ds_read_b64_tr_b16 v[224:225], v134 offset:2048
	ds_read_b64_tr_b16 v[226:227], v134 offset:4096
	ds_read_b64_tr_b16 v[228:229], v134 offset:6144
	ds_read_b64_tr_b16 v[230:231], v134 offset:8192
	ds_read_b64_tr_b16 v[232:233], v134 offset:10240
	ds_read_b64_tr_b16 v[234:235], v134 offset:12288
	ds_read_b64_tr_b16 v[236:237], v134 offset:14336
	v_mfma_f32_32x32x16_bf16 v[32:47], v[156:159], v[86:89], 0
	v_exp_f32_e32 v206, v206
	v_add_f32_e32 v133, v133, v190
	v_exp_f32_e32 v207, v207
	v_add_f32_e32 v135, v135, v191
	v_exp_f32_e32 v208, v208
	v_mfma_f32_32x32x16_bf16 v[48:63], v[160:163], v[86:89], 0
	v_add_f32_e32 v133, v133, v192
	v_exp_f32_e32 v209, v209
	v_add_f32_e32 v135, v135, v193
	v_exp_f32_e32 v210, v210
	v_add_f32_e32 v133, v133, v194
	v_mfma_f32_32x32x16_bf16 v[32:47], v[164:167], v[82:85], v[32:47]
	v_exp_f32_e32 v211, v211
	v_add_f32_e32 v135, v135, v195
	v_exp_f32_e32 v212, v212
	v_add_f32_e32 v133, v133, v196
	v_exp_f32_e32 v213, v213
	v_add_f32_e32 v135, v135, v197
	v_mfma_f32_32x32x16_bf16 v[48:63], v[168:171], v[82:85], v[48:63]
	s_waitcnt lgkmcnt(7)
	ds_read_b64_tr_b16 v[238:239], v134 offset:512
	ds_read_b64_tr_b16 v[240:241], v134 offset:2560
	ds_read_b64_tr_b16 v[242:243], v134 offset:4608
	ds_read_b64_tr_b16 v[244:245], v134 offset:6656
	ds_read_b64_tr_b16 v[246:247], v134 offset:8704
	ds_read_b64_tr_b16 v[248:249], v134 offset:10752
	ds_read_b64_tr_b16 v[140:141], v134 offset:12800
	ds_read_b64_tr_b16 v[142:143], v134 offset:14848
	v_exp_f32_e32 v214, v214
	v_add_f32_e32 v133, v133, v198
	v_exp_f32_e32 v215, v215
	v_add_f32_e32 v135, v135, v199
	v_exp_f32_e32 v216, v216
	v_mfma_f32_32x32x16_bf16 v[32:47], v[172:175], v[90:93], v[32:47]
	v_add_f32_e32 v133, v133, v200
	v_exp_f32_e32 v217, v217
	v_add_f32_e32 v135, v135, v201
	v_exp_f32_e32 v218, v218
	v_add_f32_e32 v133, v133, v202
	v_mfma_f32_32x32x16_bf16 v[48:63], v[176:179], v[90:93], v[48:63]
	v_exp_f32_e32 v219, v219
	v_add_f32_e32 v135, v135, v203
	v_exp_f32_e32 v220, v220
	v_add_f32_e32 v133, v133, v204
	v_exp_f32_e32 v221, v221
	v_add_f32_e32 v135, v135, v205
	v_mfma_f32_32x32x16_bf16 v[32:47], v[180:183], v[94:97], v[32:47]
	v_add_f32_e32 v133, v133, v206
	v_add_f32_e32 v135, v135, v207
	v_add_f32_e32 v133, v133, v208
	v_add_f32_e32 v135, v135, v209
	v_add_f32_e32 v133, v133, v210
	v_mfma_f32_32x32x16_bf16 v[48:63], v[184:187], v[94:97], v[48:63]
	v_add_f32_e32 v135, v135, v211
	v_add_f32_e32 v133, v133, v212
	v_add_f32_e32 v135, v135, v213
	v_add_f32_e32 v133, v133, v214
	v_add_f32_e32 v135, v135, v215
	v_mfma_f32_32x32x16_bf16 v[32:47], v[64:67], v[98:101], v[32:47]
	v_add_f32_e32 v133, v133, v216
	v_add_f32_e32 v135, v135, v217
	v_add_f32_e32 v133, v133, v218
	v_add_f32_e32 v135, v135, v219
	v_add_f32_e32 v133, v133, v220
	v_add_f32_e32 v135, v135, v221
	v_mfma_f32_32x32x16_bf16 v[48:63], v[68:71], v[98:101], v[48:63]
	v_cvt_pk_bf16_f32 v190, v190, v191
	v_cvt_pk_bf16_f32 v191, v192, v193
	v_cvt_pk_bf16_f32 v192, v194, v195
	v_cvt_pk_bf16_f32 v193, v196, v197
	v_cvt_pk_bf16_f32 v194, v198, v199
	v_mfma_f32_32x32x16_bf16 v[32:47], v[72:75], v[102:105], v[32:47]
	v_cvt_pk_bf16_f32 v195, v200, v201
	v_cvt_pk_bf16_f32 v196, v202, v203
	v_cvt_pk_bf16_f32 v197, v204, v205
	v_cvt_pk_bf16_f32 v206, v206, v207
	v_cvt_pk_bf16_f32 v207, v208, v209
	v_mfma_f32_32x32x16_bf16 v[48:63], v[76:79], v[102:105], v[48:63]
	v_cvt_pk_bf16_f32 v208, v210, v211
	v_cvt_pk_bf16_f32 v209, v212, v213
	v_cvt_pk_bf16_f32 v210, v214, v215
	v_cvt_pk_bf16_f32 v211, v216, v217
	v_cvt_pk_bf16_f32 v212, v218, v219
	v_cvt_pk_bf16_f32 v213, v220, v221
	s_waitcnt lgkmcnt(0)
	s_waitcnt vmcnt(3)
	s_barrier
	ds_read_b128 v[156:159], v146 offset:32768
	ds_read_b128 v[160:163], v146 offset:40960
	ds_read_b128 v[164:167], v147 offset:32768
	ds_read_b128 v[168:171], v147 offset:40960
	ds_read_b128 v[172:175], v148 offset:32768
	ds_read_b128 v[176:179], v148 offset:40960
	ds_read_b128 v[180:183], v149 offset:32768
	ds_read_b128 v[184:187], v149 offset:40960
	ds_read_b128 v[64:67], v150 offset:32768
	ds_read_b128 v[68:71], v150 offset:40960
	ds_read_b128 v[72:75], v151 offset:32768
	ds_read_b128 v[76:79], v151 offset:40960
	v_mfma_f32_32x32x16_bf16 v[0:15], v[190:193], v[222:225], v[0:15]
	s_add_i32 m0, s60, 0x4000
	v_exp_f32_e32 v32, v32
	v_exp_f32_e32 v33, v33
	v_mfma_f32_32x32x16_bf16 v[0:15], v[194:197], v[226:229], v[0:15]
	global_load_lds_dwordx4 v124, s[56:57]
	global_load_lds_dwordx4 v126, s[56:57] offset:1024
	v_exp_f32_e32 v34, v34
	v_exp_f32_e32 v35, v35
	v_mfma_f32_32x32x16_bf16 v[0:15], v[206:209], v[230:233], v[0:15]
	s_add_u32 s56, s56, 0x4000
	s_addc_u32 s57, s57, 0
	v_exp_f32_e32 v36, v36
	v_exp_f32_e32 v37, v37
	v_mfma_f32_32x32x16_bf16 v[0:15], v[210:213], v[234:237], v[0:15]
	s_add_i32 m0, s60, 0xc000
	v_exp_f32_e32 v38, v38
	v_exp_f32_e32 v39, v39
	v_mfma_f32_32x32x16_bf16 v[16:31], v[190:193], v[238:241], v[16:31]
	global_load_lds_dwordx4 v128, s[58:59]
	v_exp_f32_e32 v40, v40
	v_exp_f32_e32 v41, v41
	v_mfma_f32_32x32x16_bf16 v[16:31], v[194:197], v[242:245], v[16:31]
	s_add_u32 s58, s58, 0x2000
	s_addc_u32 s59, s59, 0
	v_exp_f32_e32 v42, v42
	v_exp_f32_e32 v43, v43
	v_mfma_f32_32x32x16_bf16 v[16:31], v[206:209], v[246:249], v[16:31]
	v_exp_f32_e32 v44, v44
	v_exp_f32_e32 v45, v45
	v_mfma_f32_32x32x16_bf16 v[16:31], v[210:213], v[140:143], v[16:31]
	v_exp_f32_e32 v46, v46
	v_exp_f32_e32 v47, v47
	s_waitcnt lgkmcnt(0)
; #define SBAR() __builtin_amdgcn_sched_barrier(0)
; #define ROT() do { const int t_ = bv; bv = bk; bk = bw; bw = t_; } while (0)
; __device__ __forceinline__ void partialSM(f32x16& p0) {
; #pragma unroll
;   for (int r = 0; r < 16; ++r) p0[r] = __builtin_amdgcn_exp2f(p0[r]);
; }
; __device__ __forceinline__ void finishSM(f32x16& p0, f32x16& p1, float& l_reg, bf16x8& pa0, bf16x8& pa1, bf16x8& pa2, bf16x8& pa3) {
; #pragma unroll
;   for (int r = 0; r < 16; ++r) p1[r] = __builtin_amdgcn_exp2f(p1[r]);
;   float ps = 0;
; #pragma unroll
;   for (int r = 0; r < 16; ++r) ps += p0[r];
; #pragma unroll
;   for (int r = 0; r < 16; ++r) ps += p1[r];
;   l_reg += ps;
;     ...
;   PK4(p0, 0, pa0); PK4(p0, 8, pa1); PK4(p1, 0, pa2); PK4(p1, 8, pa3);
;     ...
; }
; template <int ND> __device__ __forceinline__ void qkt(f32x16& p0, f32x16& p1, const bf16* Ks, const bf16x8* qr, int r32, int hi) {
;   p0 = f32x16{}; p1 = f32x16{};
; #pragma unroll
;   for (int d0 = 0; d0 < ND; ++d0) { int cb = (d0 * 16 + hi * 8) * 2;
;     bf16x8 b0 = *reinterpret_cast<const bf16x8*>((const char*)Ks + KSWZ(r32, cb));
;     bf16x8 b1 = *reinterpret_cast<const bf16x8*>((const char*)Ks + KSWZ(32 + r32, cb));
;     p0 = __builtin_amdgcn_mfma_f32_32x32x16_bf16(b0, qr[d0], p0, 0, 0, 0);
;     p1 = __builtin_amdgcn_mfma_f32_32x32x16_bf16(b1, qr[d0], p1, 0, 0, 0); }
; }
; template <bool SHIFT> __device__ __forceinline__ void attn_dense_body(const bf16* __restrict__ Qb, const bf16* __restrict__ Kh, const bf16* __restrict__ Vh, bf16* __restrict__ Ob, int seq, char* lds, LAS unsigned char* ldsl, float negB, const float* __restrict__ gq, int qpos0) {
;     ...
;   for (int j = 1; j + 1 < NT; j += 2) {
;     DMA(bw, (j + 1) * KVBLK);
;     SBAR(); qkt<SHIFT ? 7 : 6>(pB0, pB1, (bf16*)((char*)K_lds + bk * SHM_K), qr, r32, hi);
;     finishSM(pA0, pA1, l_reg, pa0, pa1, pa2, pa3); SBAR();
;     pv_d0(o, vb0 + bv * (int)SHM_V, pa0, pa1, pa2, pa3); partialSM(pB0);
;     asm volatile("s_waitcnt vmcnt(0)" ::: "memory"); __syncthreads(); ROT();
;     DMA(bw, (j + 2) * KVBLK);
;     SBAR(); qkt<SHIFT ? 7 : 6>(pA0, pA1, (bf16*)((char*)K_lds + bk * SHM_K), qr, r32, hi);
;     finishSM(pB0, pB1, l_reg, pa0, pa1, pa2, pa3); SBAR();
;     pv_d0(o, vb0 + bv * (int)SHM_V, pa0, pa1, pa2, pa3); partialSM(pA0);
;     asm volatile("s_waitcnt vmcnt(0)" ::: "memory"); __syncthreads(); ROT();
;   }
	ds_read_b64_tr_b16 v[222:223], v134 offset:16384
	ds_read_b64_tr_b16 v[224:225], v134 offset:18432
	ds_read_b64_tr_b16 v[226:227], v134 offset:20480
	ds_read_b64_tr_b16 v[228:229], v134 offset:22528
	ds_read_b64_tr_b16 v[230:231], v134 offset:24576
	ds_read_b64_tr_b16 v[232:233], v134 offset:26624
	ds_read_b64_tr_b16 v[234:235], v134 offset:28672
	ds_read_b64_tr_b16 v[236:237], v134 offset:30720
	v_mfma_f32_32x32x16_bf16 v[190:205], v[156:159], v[86:89], 0
	v_exp_f32_e32 v48, v48
	v_add_f32_e32 v133, v133, v32
	v_exp_f32_e32 v49, v49
	v_add_f32_e32 v135, v135, v33
	v_exp_f32_e32 v50, v50
	v_mfma_f32_32x32x16_bf16 v[206:221], v[160:163], v[86:89], 0
	v_add_f32_e32 v133, v133, v34
	v_exp_f32_e32 v51, v51
	v_add_f32_e32 v135, v135, v35
	v_exp_f32_e32 v52, v52
	v_add_f32_e32 v133, v133, v36
	v_mfma_f32_32x32x16_bf16 v[190:205], v[164:167], v[82:85], v[190:205]
	v_exp_f32_e32 v53, v53
	v_add_f32_e32 v135, v135, v37
	v_exp_f32_e32 v54, v54
	v_add_f32_e32 v133, v133, v38
	v_exp_f32_e32 v55, v55
	v_add_f32_e32 v135, v135, v39
	v_mfma_f32_32x32x16_bf16 v[206:221], v[168:171], v[82:85], v[206:221]
	s_waitcnt lgkmcnt(7)
	ds_read_b64_tr_b16 v[238:239], v134 offset:16896
	ds_read_b64_tr_b16 v[240:241], v134 offset:18944
	ds_read_b64_tr_b16 v[242:243], v134 offset:20992
	ds_read_b64_tr_b16 v[244:245], v134 offset:23040
	ds_read_b64_tr_b16 v[246:247], v134 offset:25088
	ds_read_b64_tr_b16 v[248:249], v134 offset:27136
	ds_read_b64_tr_b16 v[140:141], v134 offset:29184
	ds_read_b64_tr_b16 v[142:143], v134 offset:31232
	v_exp_f32_e32 v56, v56
	v_add_f32_e32 v133, v133, v40
	v_exp_f32_e32 v57, v57
	v_add_f32_e32 v135, v135, v41
	v_exp_f32_e32 v58, v58
	v_mfma_f32_32x32x16_bf16 v[190:205], v[172:175], v[90:93], v[190:205]
	v_add_f32_e32 v133, v133, v42
	v_exp_f32_e32 v59, v59
	v_add_f32_e32 v135, v135, v43
	v_exp_f32_e32 v60, v60
	v_add_f32_e32 v133, v133, v44
	v_mfma_f32_32x32x16_bf16 v[206:221], v[176:179], v[90:93], v[206:221]
	v_exp_f32_e32 v61, v61
	v_add_f32_e32 v135, v135, v45
	v_exp_f32_e32 v62, v62
	v_add_f32_e32 v133, v133, v46
	v_exp_f32_e32 v63, v63
	v_add_f32_e32 v135, v135, v47
	v_mfma_f32_32x32x16_bf16 v[190:205], v[180:183], v[94:97], v[190:205]
	v_add_f32_e32 v133, v133, v48
	v_add_f32_e32 v135, v135, v49
	v_add_f32_e32 v133, v133, v50
	v_add_f32_e32 v135, v135, v51
	v_add_f32_e32 v133, v133, v52
	v_mfma_f32_32x32x16_bf16 v[206:221], v[184:187], v[94:97], v[206:221]
	v_add_f32_e32 v135, v135, v53
	v_add_f32_e32 v133, v133, v54
	v_add_f32_e32 v135, v135, v55
	v_add_f32_e32 v133, v133, v56
	v_add_f32_e32 v135, v135, v57
	v_mfma_f32_32x32x16_bf16 v[190:205], v[64:67], v[98:101], v[190:205]
	v_add_f32_e32 v133, v133, v58
	v_add_f32_e32 v135, v135, v59
	v_add_f32_e32 v133, v133, v60
	v_add_f32_e32 v135, v135, v61
	v_add_f32_e32 v133, v133, v62
	v_add_f32_e32 v135, v135, v63
	v_mfma_f32_32x32x16_bf16 v[206:221], v[68:71], v[98:101], v[206:221]
	v_cvt_pk_bf16_f32 v32, v32, v33
	v_cvt_pk_bf16_f32 v33, v34, v35
	v_cvt_pk_bf16_f32 v34, v36, v37
	v_cvt_pk_bf16_f32 v35, v38, v39
	v_cvt_pk_bf16_f32 v36, v40, v41
	v_mfma_f32_32x32x16_bf16 v[190:205], v[72:75], v[102:105], v[190:205]
	v_cvt_pk_bf16_f32 v37, v42, v43
	v_cvt_pk_bf16_f32 v38, v44, v45
	v_cvt_pk_bf16_f32 v39, v46, v47
	v_cvt_pk_bf16_f32 v48, v48, v49
	v_cvt_pk_bf16_f32 v49, v50, v51
	v_mfma_f32_32x32x16_bf16 v[206:221], v[76:79], v[102:105], v[206:221]
	v_cvt_pk_bf16_f32 v50, v52, v53
	v_cvt_pk_bf16_f32 v51, v54, v55
	v_cvt_pk_bf16_f32 v52, v56, v57
	v_cvt_pk_bf16_f32 v53, v58, v59
	v_cvt_pk_bf16_f32 v54, v60, v61
	v_cvt_pk_bf16_f32 v55, v62, v63
	s_waitcnt lgkmcnt(0)
	s_waitcnt vmcnt(3)
	s_barrier
	ds_read_b128 v[156:159], v146 offset:0
	ds_read_b128 v[160:163], v146 offset:8192
	ds_read_b128 v[164:167], v147 offset:0
	ds_read_b128 v[168:171], v147 offset:8192
	ds_read_b128 v[172:175], v148 offset:0
	ds_read_b128 v[176:179], v148 offset:8192
	ds_read_b128 v[180:183], v149 offset:0
	ds_read_b128 v[184:187], v149 offset:8192
	ds_read_b128 v[64:67], v150 offset:0
	ds_read_b128 v[68:71], v150 offset:8192
	ds_read_b128 v[72:75], v151 offset:0
	ds_read_b128 v[76:79], v151 offset:8192
	v_mfma_f32_32x32x16_bf16 v[0:15], v[32:35], v[222:225], v[0:15]
	s_add_i32 m0, s60, 0x8000
	v_exp_f32_e32 v190, v190
	v_exp_f32_e32 v191, v191
	v_mfma_f32_32x32x16_bf16 v[0:15], v[36:39], v[226:229], v[0:15]
	global_load_lds_dwordx4 v124, s[56:57]
	global_load_lds_dwordx4 v126, s[56:57] offset:1024
	v_exp_f32_e32 v192, v192
	v_exp_f32_e32 v193, v193
	v_mfma_f32_32x32x16_bf16 v[0:15], v[48:51], v[230:233], v[0:15]
	s_add_u32 s56, s56, 0x4000
	s_addc_u32 s57, s57, 0
	v_exp_f32_e32 v194, v194
	v_exp_f32_e32 v195, v195
	v_mfma_f32_32x32x16_bf16 v[0:15], v[52:55], v[234:237], v[0:15]
	s_add_i32 m0, s60, 0x10000
	v_exp_f32_e32 v196, v196
	v_exp_f32_e32 v197, v197
	v_mfma_f32_32x32x16_bf16 v[16:31], v[32:35], v[238:241], v[16:31]
	global_load_lds_dwordx4 v128, s[58:59]
	v_exp_f32_e32 v198, v198
	v_exp_f32_e32 v199, v199
	v_mfma_f32_32x32x16_bf16 v[16:31], v[36:39], v[242:245], v[16:31]
	s_add_u32 s58, s58, 0x2000
	s_addc_u32 s59, s59, 0
	v_exp_f32_e32 v200, v200
	v_exp_f32_e32 v201, v201
	v_mfma_f32_32x32x16_bf16 v[16:31], v[48:51], v[246:249], v[16:31]
	v_exp_f32_e32 v202, v202
	v_exp_f32_e32 v203, v203
	v_mfma_f32_32x32x16_bf16 v[16:31], v[52:55], v[140:143], v[16:31]
	v_exp_f32_e32 v204, v204
	v_exp_f32_e32 v205, v205
	s_waitcnt lgkmcnt(0)
; #define SBAR() __builtin_amdgcn_sched_barrier(0)
; #define ROT() do { const int t_ = bv; bv = bk; bk = bw; bw = t_; } while (0)
; __device__ __forceinline__ void partialSM(f32x16& p0) {
; #pragma unroll
;   for (int r = 0; r < 16; ++r) p0[r] = __builtin_amdgcn_exp2f(p0[r]);
; }
; __device__ __forceinline__ void finishSM(f32x16& p0, f32x16& p1, float& l_reg, bf16x8& pa0, bf16x8& pa1, bf16x8& pa2, bf16x8& pa3) {
; #pragma unroll
;   for (int r = 0; r < 16; ++r) p1[r] = __builtin_amdgcn_exp2f(p1[r]);
;   float ps = 0;
; #pragma unroll
;   for (int r = 0; r < 16; ++r) ps += p0[r];
; #pragma unroll
;   for (int r = 0; r < 16; ++r) ps += p1[r];
;   l_reg += ps;
;     ...
;   PK4(p0, 0, pa0); PK4(p0, 8, pa1); PK4(p1, 0, pa2); PK4(p1, 8, pa3);
;     ...
; }
; template <int ND> __device__ __forceinline__ void qkt(f32x16& p0, f32x16& p1, const bf16* Ks, const bf16x8* qr, int r32, int hi) {
;   p0 = f32x16{}; p1 = f32x16{};
; #pragma unroll
;   for (int d0 = 0; d0 < ND; ++d0) { int cb = (d0 * 16 + hi * 8) * 2;
;     bf16x8 b0 = *reinterpret_cast<const bf16x8*>((const char*)Ks + KSWZ(r32, cb));
;     bf16x8 b1 = *reinterpret_cast<const bf16x8*>((const char*)Ks + KSWZ(32 + r32, cb));
;     p0 = __builtin_amdgcn_mfma_f32_32x32x16_bf16(b0, qr[d0], p0, 0, 0, 0);
;     p1 = __builtin_amdgcn_mfma_f32_32x32x16_bf16(b1, qr[d0], p1, 0, 0, 0); }
; }
; template <bool SHIFT> __device__ __forceinline__ void attn_dense_body(const bf16* __restrict__ Qb, const bf16* __restrict__ Kh, const bf16* __restrict__ Vh, bf16* __restrict__ Ob, int seq, char* lds, LAS unsigned char* ldsl, float negB, const float* __restrict__ gq, int qpos0) {
;     ...
;   for (int j = 1; j + 1 < NT; j += 2) {
;     DMA(bw, (j + 1) * KVBLK);
;     SBAR(); qkt<SHIFT ? 7 : 6>(pB0, pB1, (bf16*)((char*)K_lds + bk * SHM_K), qr, r32, hi);
;     finishSM(pA0, pA1, l_reg, pa0, pa1, pa2, pa3); SBAR();
;     pv_d0(o, vb0 + bv * (int)SHM_V, pa0, pa1, pa2, pa3); partialSM(pB0);
;     asm volatile("s_waitcnt vmcnt(0)" ::: "memory"); __syncthreads(); ROT();
;     DMA(bw, (j + 2) * KVBLK);
;     SBAR(); qkt<SHIFT ? 7 : 6>(pA0, pA1, (bf16*)((char*)K_lds + bk * SHM_K), qr, r32, hi);
;     finishSM(pB0, pB1, l_reg, pa0, pa1, pa2, pa3); SBAR();
;     pv_d0(o, vb0 + bv * (int)SHM_V, pa0, pa1, pa2, pa3); partialSM(pA0);
;     asm volatile("s_waitcnt vmcnt(0)" ::: "memory"); __syncthreads(); ROT();
;   }
	ds_read_b64_tr_b16 v[222:223], v134 offset:32768
	ds_read_b64_tr_b16 v[224:225], v134 offset:34816
	ds_read_b64_tr_b16 v[226:227], v134 offset:36864
	ds_read_b64_tr_b16 v[228:229], v134 offset:38912
	ds_read_b64_tr_b16 v[230:231], v134 offset:40960
	ds_read_b64_tr_b16 v[232:233], v134 offset:43008
	ds_read_b64_tr_b16 v[234:235], v134 offset:45056
	ds_read_b64_tr_b16 v[236:237], v134 offset:47104
	v_mfma_f32_32x32x16_bf16 v[32:47], v[156:159], v[86:89], 0
	v_exp_f32_e32 v206, v206
	v_add_f32_e32 v133, v133, v190
	v_exp_f32_e32 v207, v207
	v_add_f32_e32 v135, v135, v191
	v_exp_f32_e32 v208, v208
	v_mfma_f32_32x32x16_bf16 v[48:63], v[160:163], v[86:89], 0
	v_add_f32_e32 v133, v133, v192
	v_exp_f32_e32 v209, v209
	v_add_f32_e32 v135, v135, v193
	v_exp_f32_e32 v210, v210
	v_add_f32_e32 v133, v133, v194
	v_mfma_f32_32x32x16_bf16 v[32:47], v[164:167], v[82:85], v[32:47]
	v_exp_f32_e32 v211, v211
	v_add_f32_e32 v135, v135, v195
	v_exp_f32_e32 v212, v212
	v_add_f32_e32 v133, v133, v196
	v_exp_f32_e32 v213, v213
	v_add_f32_e32 v135, v135, v197
	v_mfma_f32_32x32x16_bf16 v[48:63], v[168:171], v[82:85], v[48:63]
	s_waitcnt lgkmcnt(7)
	ds_read_b64_tr_b16 v[238:239], v134 offset:33280
	ds_read_b64_tr_b16 v[240:241], v134 offset:35328
	ds_read_b64_tr_b16 v[242:243], v134 offset:37376
	ds_read_b64_tr_b16 v[244:245], v134 offset:39424
	ds_read_b64_tr_b16 v[246:247], v134 offset:41472
	ds_read_b64_tr_b16 v[248:249], v134 offset:43520
	ds_read_b64_tr_b16 v[140:141], v134 offset:45568
	ds_read_b64_tr_b16 v[142:143], v134 offset:47616
	v_exp_f32_e32 v214, v214
	v_add_f32_e32 v133, v133, v198
	v_exp_f32_e32 v215, v215
	v_add_f32_e32 v135, v135, v199
	v_exp_f32_e32 v216, v216
	v_mfma_f32_32x32x16_bf16 v[32:47], v[172:175], v[90:93], v[32:47]
	v_add_f32_e32 v133, v133, v200
	v_exp_f32_e32 v217, v217
	v_add_f32_e32 v135, v135, v201
	v_exp_f32_e32 v218, v218
	v_add_f32_e32 v133, v133, v202
	v_mfma_f32_32x32x16_bf16 v[48:63], v[176:179], v[90:93], v[48:63]
	v_exp_f32_e32 v219, v219
	v_add_f32_e32 v135, v135, v203
	v_exp_f32_e32 v220, v220
	v_add_f32_e32 v133, v133, v204
	v_exp_f32_e32 v221, v221
	v_add_f32_e32 v135, v135, v205
	v_mfma_f32_32x32x16_bf16 v[32:47], v[180:183], v[94:97], v[32:47]
	v_add_f32_e32 v133, v133, v206
	v_add_f32_e32 v135, v135, v207
	v_add_f32_e32 v133, v133, v208
	v_add_f32_e32 v135, v135, v209
	v_add_f32_e32 v133, v133, v210
	v_mfma_f32_32x32x16_bf16 v[48:63], v[184:187], v[94:97], v[48:63]
	v_add_f32_e32 v135, v135, v211
	v_add_f32_e32 v133, v133, v212
	v_add_f32_e32 v135, v135, v213
	v_add_f32_e32 v133, v133, v214
	v_add_f32_e32 v135, v135, v215
	v_mfma_f32_32x32x16_bf16 v[32:47], v[64:67], v[98:101], v[32:47]
	v_add_f32_e32 v133, v133, v216
	v_add_f32_e32 v135, v135, v217
	v_add_f32_e32 v133, v133, v218
	v_add_f32_e32 v135, v135, v219
	v_add_f32_e32 v133, v133, v220
	v_add_f32_e32 v135, v135, v221
	v_mfma_f32_32x32x16_bf16 v[48:63], v[68:71], v[98:101], v[48:63]
	v_cvt_pk_bf16_f32 v190, v190, v191
	v_cvt_pk_bf16_f32 v191, v192, v193
	v_cvt_pk_bf16_f32 v192, v194, v195
	v_cvt_pk_bf16_f32 v193, v196, v197
	v_cvt_pk_bf16_f32 v194, v198, v199
	v_mfma_f32_32x32x16_bf16 v[32:47], v[72:75], v[102:105], v[32:47]
	v_cvt_pk_bf16_f32 v195, v200, v201
	v_cvt_pk_bf16_f32 v196, v202, v203
	v_cvt_pk_bf16_f32 v197, v204, v205
	v_cvt_pk_bf16_f32 v206, v206, v207
	v_cvt_pk_bf16_f32 v207, v208, v209
	v_mfma_f32_32x32x16_bf16 v[48:63], v[76:79], v[102:105], v[48:63]
	v_cvt_pk_bf16_f32 v208, v210, v211
	v_cvt_pk_bf16_f32 v209, v212, v213
	v_cvt_pk_bf16_f32 v210, v214, v215
	v_cvt_pk_bf16_f32 v211, v216, v217
	v_cvt_pk_bf16_f32 v212, v218, v219
	v_cvt_pk_bf16_f32 v213, v220, v221
	s_waitcnt lgkmcnt(0)
	s_waitcnt vmcnt(3)
	s_barrier
	ds_read_b128 v[156:159], v146 offset:16384
	ds_read_b128 v[160:163], v146 offset:24576
	ds_read_b128 v[164:167], v147 offset:16384
	ds_read_b128 v[168:171], v147 offset:24576
	ds_read_b128 v[172:175], v148 offset:16384
	ds_read_b128 v[176:179], v148 offset:24576
	ds_read_b128 v[180:183], v149 offset:16384
	ds_read_b128 v[184:187], v149 offset:24576
	ds_read_b128 v[64:67], v150 offset:16384
	ds_read_b128 v[68:71], v150 offset:24576
	ds_read_b128 v[72:75], v151 offset:16384
	ds_read_b128 v[76:79], v151 offset:24576
	v_mfma_f32_32x32x16_bf16 v[0:15], v[190:193], v[222:225], v[0:15]
	s_add_i32 m0, s60, 0x0
	v_exp_f32_e32 v32, v32
	v_exp_f32_e32 v33, v33
	v_mfma_f32_32x32x16_bf16 v[0:15], v[194:197], v[226:229], v[0:15]
	global_load_lds_dwordx4 v124, s[56:57]
	global_load_lds_dwordx4 v126, s[56:57] offset:1024
	v_exp_f32_e32 v34, v34
	v_exp_f32_e32 v35, v35
	v_mfma_f32_32x32x16_bf16 v[0:15], v[206:209], v[230:233], v[0:15]
	s_add_u32 s56, s56, 0x4000
	s_addc_u32 s57, s57, 0
	v_exp_f32_e32 v36, v36
	v_exp_f32_e32 v37, v37
	v_mfma_f32_32x32x16_bf16 v[0:15], v[210:213], v[234:237], v[0:15]
	s_add_i32 m0, s60, 0x14000
	v_exp_f32_e32 v38, v38
	v_exp_f32_e32 v39, v39
	v_mfma_f32_32x32x16_bf16 v[16:31], v[190:193], v[238:241], v[16:31]
	global_load_lds_dwordx4 v128, s[58:59]
	v_exp_f32_e32 v40, v40
	v_exp_f32_e32 v41, v41
	v_mfma_f32_32x32x16_bf16 v[16:31], v[194:197], v[242:245], v[16:31]
	s_add_u32 s58, s58, 0x2000
	s_addc_u32 s59, s59, 0
	v_exp_f32_e32 v42, v42
	v_exp_f32_e32 v43, v43
	v_mfma_f32_32x32x16_bf16 v[16:31], v[206:209], v[246:249], v[16:31]
	v_exp_f32_e32 v44, v44
	v_exp_f32_e32 v45, v45
	v_mfma_f32_32x32x16_bf16 v[16:31], v[210:213], v[140:143], v[16:31]
	v_exp_f32_e32 v46, v46
	v_exp_f32_e32 v47, v47
	s_sub_u32 s33, s33, 1
	s_cmp_lg_u32 s33, 0
	s_cbranch_scc1 .Latt_loop
; #define SBAR() __builtin_amdgcn_sched_barrier(0)
; #define ROT() do { const int t_ = bv; bv = bk; bk = bw; bw = t_; } while (0)
; __device__ __forceinline__ void partialSM(f32x16& p0) {
; #pragma unroll
;   for (int r = 0; r < 16; ++r) p0[r] = __builtin_amdgcn_exp2f(p0[r]);
; }
; __device__ __forceinline__ void finishSM(f32x16& p0, f32x16& p1, float& l_reg, bf16x8& pa0, bf16x8& pa1, bf16x8& pa2, bf16x8& pa3) {
; #pragma unroll
;   for (int r = 0; r < 16; ++r) p1[r] = __builtin_amdgcn_exp2f(p1[r]);
;   float ps = 0;
; #pragma unroll
;   for (int r = 0; r < 16; ++r) ps += p0[r];
; #pragma unroll
;   for (int r = 0; r < 16; ++r) ps += p1[r];
;   l_reg += ps;
;     ...
;   PK4(p0, 0, pa0); PK4(p0, 8, pa1); PK4(p1, 0, pa2); PK4(p1, 8, pa3);
;     ...
; }
; template <int ND> __device__ __forceinline__ void qkt(f32x16& p0, f32x16& p1, const bf16* Ks, const bf16x8* qr, int r32, int hi) {
;   p0 = f32x16{}; p1 = f32x16{};
; #pragma unroll
;   for (int d0 = 0; d0 < ND; ++d0) { int cb = (d0 * 16 + hi * 8) * 2;
;     bf16x8 b0 = *reinterpret_cast<const bf16x8*>((const char*)Ks + KSWZ(r32, cb));
;     bf16x8 b1 = *reinterpret_cast<const bf16x8*>((const char*)Ks + KSWZ(32 + r32, cb));
;     p0 = __builtin_amdgcn_mfma_f32_32x32x16_bf16(b0, qr[d0], p0, 0, 0, 0);
;     p1 = __builtin_amdgcn_mfma_f32_32x32x16_bf16(b1, qr[d0], p1, 0, 0, 0); }
; }
; template <bool SHIFT> __device__ __forceinline__ void attn_dense_body(const bf16* __restrict__ Qb, const bf16* __restrict__ Kh, const bf16* __restrict__ Vh, bf16* __restrict__ Ob, int seq, char* lds, LAS unsigned char* ldsl, float negB, const float* __restrict__ gq, int qpos0) {
;     ...
;   for (int j = 1; j + 1 < NT; j += 2) {
;     DMA(bw, (j + 1) * KVBLK);
;     SBAR(); qkt<SHIFT ? 7 : 6>(pB0, pB1, (bf16*)((char*)K_lds + bk * SHM_K), qr, r32, hi);
;     finishSM(pA0, pA1, l_reg, pa0, pa1, pa2, pa3); SBAR();
;     pv_d0(o, vb0 + bv * (int)SHM_V, pa0, pa1, pa2, pa3); partialSM(pB0);
;     asm volatile("s_waitcnt vmcnt(0)" ::: "memory"); __syncthreads(); ROT();
;     DMA(bw, (j + 2) * KVBLK);
;     SBAR(); qkt<SHIFT ? 7 : 6>(pA0, pA1, (bf16*)((char*)K_lds + bk * SHM_K), qr, r32, hi);
;     finishSM(pB0, pB1, l_reg, pa0, pa1, pa2, pa3); SBAR();
;     pv_d0(o, vb0 + bv * (int)SHM_V, pa0, pa1, pa2, pa3); partialSM(pA0);
;     asm volatile("s_waitcnt vmcnt(0)" ::: "memory"); __syncthreads(); ROT();
;   }
	s_waitcnt lgkmcnt(0)
	ds_read_b64_tr_b16 v[222:223], v134 offset:0
	ds_read_b64_tr_b16 v[224:225], v134 offset:2048
	ds_read_b64_tr_b16 v[226:227], v134 offset:4096
	ds_read_b64_tr_b16 v[228:229], v134 offset:6144
	ds_read_b64_tr_b16 v[230:231], v134 offset:8192
	ds_read_b64_tr_b16 v[232:233], v134 offset:10240
	ds_read_b64_tr_b16 v[234:235], v134 offset:12288
	ds_read_b64_tr_b16 v[236:237], v134 offset:14336
	v_mfma_f32_32x32x16_bf16 v[190:205], v[156:159], v[86:89], 0
	v_exp_f32_e32 v48, v48
	v_add_f32_e32 v133, v133, v32
	v_exp_f32_e32 v49, v49
	v_add_f32_e32 v135, v135, v33
	v_exp_f32_e32 v50, v50
	v_mfma_f32_32x32x16_bf16 v[206:221], v[160:163], v[86:89], 0
	v_add_f32_e32 v133, v133, v34
	v_exp_f32_e32 v51, v51
	v_add_f32_e32 v135, v135, v35
	v_exp_f32_e32 v52, v52
	v_add_f32_e32 v133, v133, v36
	v_mfma_f32_32x32x16_bf16 v[190:205], v[164:167], v[82:85], v[190:205]
	v_exp_f32_e32 v53, v53
	v_add_f32_e32 v135, v135, v37
	v_exp_f32_e32 v54, v54
	v_add_f32_e32 v133, v133, v38
	v_exp_f32_e32 v55, v55
	v_add_f32_e32 v135, v135, v39
	v_mfma_f32_32x32x16_bf16 v[206:221], v[168:171], v[82:85], v[206:221]
	s_waitcnt lgkmcnt(7)
	ds_read_b64_tr_b16 v[238:239], v134 offset:512
	ds_read_b64_tr_b16 v[240:241], v134 offset:2560
	ds_read_b64_tr_b16 v[242:243], v134 offset:4608
	ds_read_b64_tr_b16 v[244:245], v134 offset:6656
	ds_read_b64_tr_b16 v[246:247], v134 offset:8704
	ds_read_b64_tr_b16 v[248:249], v134 offset:10752
	ds_read_b64_tr_b16 v[140:141], v134 offset:12800
	ds_read_b64_tr_b16 v[142:143], v134 offset:14848
	v_exp_f32_e32 v56, v56
	v_add_f32_e32 v133, v133, v40
	v_exp_f32_e32 v57, v57
	v_add_f32_e32 v135, v135, v41
	v_exp_f32_e32 v58, v58
	v_mfma_f32_32x32x16_bf16 v[190:205], v[172:175], v[90:93], v[190:205]
	v_add_f32_e32 v133, v133, v42
	v_exp_f32_e32 v59, v59
	v_add_f32_e32 v135, v135, v43
	v_exp_f32_e32 v60, v60
	v_add_f32_e32 v133, v133, v44
	v_mfma_f32_32x32x16_bf16 v[206:221], v[176:179], v[90:93], v[206:221]
	v_exp_f32_e32 v61, v61
	v_add_f32_e32 v135, v135, v45
	v_exp_f32_e32 v62, v62
	v_add_f32_e32 v133, v133, v46
	v_exp_f32_e32 v63, v63
	v_add_f32_e32 v135, v135, v47
	v_mfma_f32_32x32x16_bf16 v[190:205], v[180:183], v[94:97], v[190:205]
	v_add_f32_e32 v133, v133, v48
	v_add_f32_e32 v135, v135, v49
	v_add_f32_e32 v133, v133, v50
	v_add_f32_e32 v135, v135, v51
	v_add_f32_e32 v133, v133, v52
	v_mfma_f32_32x32x16_bf16 v[206:221], v[184:187], v[94:97], v[206:221]
	v_add_f32_e32 v135, v135, v53
	v_add_f32_e32 v133, v133, v54
	v_add_f32_e32 v135, v135, v55
	v_add_f32_e32 v133, v133, v56
	v_add_f32_e32 v135, v135, v57
	v_mfma_f32_32x32x16_bf16 v[190:205], v[64:67], v[98:101], v[190:205]
	v_add_f32_e32 v133, v133, v58
	v_add_f32_e32 v135, v135, v59
	v_add_f32_e32 v133, v133, v60
	v_add_f32_e32 v135, v135, v61
	v_add_f32_e32 v133, v133, v62
	v_add_f32_e32 v135, v135, v63
	v_mfma_f32_32x32x16_bf16 v[206:221], v[68:71], v[98:101], v[206:221]
	v_cvt_pk_bf16_f32 v32, v32, v33
	v_cvt_pk_bf16_f32 v33, v34, v35
	v_cvt_pk_bf16_f32 v34, v36, v37
	v_cvt_pk_bf16_f32 v35, v38, v39
	v_cvt_pk_bf16_f32 v36, v40, v41
	v_mfma_f32_32x32x16_bf16 v[190:205], v[72:75], v[102:105], v[190:205]
	v_cvt_pk_bf16_f32 v37, v42, v43
	v_cvt_pk_bf16_f32 v38, v44, v45
	v_cvt_pk_bf16_f32 v39, v46, v47
	v_cvt_pk_bf16_f32 v48, v48, v49
	v_cvt_pk_bf16_f32 v49, v50, v51
	v_mfma_f32_32x32x16_bf16 v[206:221], v[76:79], v[102:105], v[206:221]
	v_cvt_pk_bf16_f32 v50, v52, v53
	v_cvt_pk_bf16_f32 v51, v54, v55
	v_cvt_pk_bf16_f32 v52, v56, v57
	v_cvt_pk_bf16_f32 v53, v58, v59
	v_cvt_pk_bf16_f32 v54, v60, v61
	v_cvt_pk_bf16_f32 v55, v62, v63
	s_waitcnt lgkmcnt(0)
	s_waitcnt vmcnt(3)
	s_barrier
	ds_read_b128 v[156:159], v146 offset:32768
	ds_read_b128 v[160:163], v146 offset:40960
	ds_read_b128 v[164:167], v147 offset:32768
	ds_read_b128 v[168:171], v147 offset:40960
	ds_read_b128 v[172:175], v148 offset:32768
	ds_read_b128 v[176:179], v148 offset:40960
	ds_read_b128 v[180:183], v149 offset:32768
	ds_read_b128 v[184:187], v149 offset:40960
	ds_read_b128 v[64:67], v150 offset:32768
	ds_read_b128 v[68:71], v150 offset:40960
	ds_read_b128 v[72:75], v151 offset:32768
	ds_read_b128 v[76:79], v151 offset:40960
	v_mfma_f32_32x32x16_bf16 v[0:15], v[32:35], v[222:225], v[0:15]
	s_add_i32 m0, s60, 0x4000
	v_exp_f32_e32 v190, v190
	v_exp_f32_e32 v191, v191
	v_mfma_f32_32x32x16_bf16 v[0:15], v[36:39], v[226:229], v[0:15]
	global_load_lds_dwordx4 v124, s[56:57]
	global_load_lds_dwordx4 v126, s[56:57] offset:1024
	v_exp_f32_e32 v192, v192
	v_exp_f32_e32 v193, v193
	v_mfma_f32_32x32x16_bf16 v[0:15], v[48:51], v[230:233], v[0:15]
	s_add_u32 s56, s56, 0x4000
	s_addc_u32 s57, s57, 0
	v_exp_f32_e32 v194, v194
	v_exp_f32_e32 v195, v195
	v_mfma_f32_32x32x16_bf16 v[0:15], v[52:55], v[234:237], v[0:15]
	s_add_i32 m0, s60, 0xc000
	v_exp_f32_e32 v196, v196
	v_exp_f32_e32 v197, v197
	v_mfma_f32_32x32x16_bf16 v[16:31], v[32:35], v[238:241], v[16:31]
	global_load_lds_dwordx4 v128, s[58:59]
	v_exp_f32_e32 v198, v198
	v_exp_f32_e32 v199, v199
	v_mfma_f32_32x32x16_bf16 v[16:31], v[36:39], v[242:245], v[16:31]
	s_add_u32 s58, s58, 0x2000
	s_addc_u32 s59, s59, 0
	v_exp_f32_e32 v200, v200
	v_exp_f32_e32 v201, v201
	v_mfma_f32_32x32x16_bf16 v[16:31], v[48:51], v[246:249], v[16:31]
	v_exp_f32_e32 v202, v202
	v_exp_f32_e32 v203, v203
	v_mfma_f32_32x32x16_bf16 v[16:31], v[52:55], v[140:143], v[16:31]
	v_exp_f32_e32 v204, v204
	v_exp_f32_e32 v205, v205
	s_waitcnt lgkmcnt(0)
; #define SBAR() __builtin_amdgcn_sched_barrier(0)
; #define ROT() do { const int t_ = bv; bv = bk; bk = bw; bw = t_; } while (0)
; __device__ __forceinline__ void partialSM(f32x16& p0) {
; #pragma unroll
;   for (int r = 0; r < 16; ++r) p0[r] = __builtin_amdgcn_exp2f(p0[r]);
; }
; __device__ __forceinline__ void finishSM(f32x16& p0, f32x16& p1, float& l_reg, bf16x8& pa0, bf16x8& pa1, bf16x8& pa2, bf16x8& pa3) {
; #pragma unroll
;   for (int r = 0; r < 16; ++r) p1[r] = __builtin_amdgcn_exp2f(p1[r]);
;   float ps = 0;
; #pragma unroll
;   for (int r = 0; r < 16; ++r) ps += p0[r];
; #pragma unroll
;   for (int r = 0; r < 16; ++r) ps += p1[r];
;   l_reg += ps;
;     ...
;   PK4(p0, 0, pa0); PK4(p0, 8, pa1); PK4(p1, 0, pa2); PK4(p1, 8, pa3);
;     ...
; }
; template <int ND> __device__ __forceinline__ void qkt(f32x16& p0, f32x16& p1, const bf16* Ks, const bf16x8* qr, int r32, int hi) {
;   p0 = f32x16{}; p1 = f32x16{};
; #pragma unroll
;   for (int d0 = 0; d0 < ND; ++d0) { int cb = (d0 * 16 + hi * 8) * 2;
;     bf16x8 b0 = *reinterpret_cast<const bf16x8*>((const char*)Ks + KSWZ(r32, cb));
;     bf16x8 b1 = *reinterpret_cast<const bf16x8*>((const char*)Ks + KSWZ(32 + r32, cb));
;     p0 = __builtin_amdgcn_mfma_f32_32x32x16_bf16(b0, qr[d0], p0, 0, 0, 0);
;     p1 = __builtin_amdgcn_mfma_f32_32x32x16_bf16(b1, qr[d0], p1, 0, 0, 0); }
; }
; template <bool SHIFT> __device__ __forceinline__ void attn_dense_body(const bf16* __restrict__ Qb, const bf16* __restrict__ Kh, const bf16* __restrict__ Vh, bf16* __restrict__ Ob, int seq, char* lds, LAS unsigned char* ldsl, float negB, const float* __restrict__ gq, int qpos0) {
;     ...
;   for (int j = 1; j + 1 < NT; j += 2) {
;     DMA(bw, (j + 1) * KVBLK);
;     SBAR(); qkt<SHIFT ? 7 : 6>(pB0, pB1, (bf16*)((char*)K_lds + bk * SHM_K), qr, r32, hi);
;     finishSM(pA0, pA1, l_reg, pa0, pa1, pa2, pa3); SBAR();
;     pv_d0(o, vb0 + bv * (int)SHM_V, pa0, pa1, pa2, pa3); partialSM(pB0);
;     asm volatile("s_waitcnt vmcnt(0)" ::: "memory"); __syncthreads(); ROT();
;     DMA(bw, (j + 2) * KVBLK);
;     SBAR(); qkt<SHIFT ? 7 : 6>(pA0, pA1, (bf16*)((char*)K_lds + bk * SHM_K), qr, r32, hi);
;     finishSM(pB0, pB1, l_reg, pa0, pa1, pa2, pa3); SBAR();
;     pv_d0(o, vb0 + bv * (int)SHM_V, pa0, pa1, pa2, pa3); partialSM(pA0);
;     asm volatile("s_waitcnt vmcnt(0)" ::: "memory"); __syncthreads(); ROT();
;   }
	ds_read_b64_tr_b16 v[222:223], v134 offset:16384
	ds_read_b64_tr_b16 v[224:225], v134 offset:18432
	ds_read_b64_tr_b16 v[226:227], v134 offset:20480
	ds_read_b64_tr_b16 v[228:229], v134 offset:22528
	ds_read_b64_tr_b16 v[230:231], v134 offset:24576
	ds_read_b64_tr_b16 v[232:233], v134 offset:26624
	ds_read_b64_tr_b16 v[234:235], v134 offset:28672
	ds_read_b64_tr_b16 v[236:237], v134 offset:30720
	v_mfma_f32_32x32x16_bf16 v[32:47], v[156:159], v[86:89], 0
	v_exp_f32_e32 v206, v206
	v_add_f32_e32 v133, v133, v190
	v_exp_f32_e32 v207, v207
	v_add_f32_e32 v135, v135, v191
	v_exp_f32_e32 v208, v208
	v_mfma_f32_32x32x16_bf16 v[48:63], v[160:163], v[86:89], 0
	v_add_f32_e32 v133, v133, v192
	v_exp_f32_e32 v209, v209
	v_add_f32_e32 v135, v135, v193
	v_exp_f32_e32 v210, v210
	v_add_f32_e32 v133, v133, v194
	v_mfma_f32_32x32x16_bf16 v[32:47], v[164:167], v[82:85], v[32:47]
	v_exp_f32_e32 v211, v211
	v_add_f32_e32 v135, v135, v195
	v_exp_f32_e32 v212, v212
	v_add_f32_e32 v133, v133, v196
	v_exp_f32_e32 v213, v213
	v_add_f32_e32 v135, v135, v197
	v_mfma_f32_32x32x16_bf16 v[48:63], v[168:171], v[82:85], v[48:63]
	s_waitcnt lgkmcnt(7)
	ds_read_b64_tr_b16 v[238:239], v134 offset:16896
	ds_read_b64_tr_b16 v[240:241], v134 offset:18944
	ds_read_b64_tr_b16 v[242:243], v134 offset:20992
	ds_read_b64_tr_b16 v[244:245], v134 offset:23040
	ds_read_b64_tr_b16 v[246:247], v134 offset:25088
	ds_read_b64_tr_b16 v[248:249], v134 offset:27136
	ds_read_b64_tr_b16 v[140:141], v134 offset:29184
	ds_read_b64_tr_b16 v[142:143], v134 offset:31232
	v_exp_f32_e32 v214, v214
	v_add_f32_e32 v133, v133, v198
	v_exp_f32_e32 v215, v215
	v_add_f32_e32 v135, v135, v199
	v_exp_f32_e32 v216, v216
	v_mfma_f32_32x32x16_bf16 v[32:47], v[172:175], v[90:93], v[32:47]
	v_add_f32_e32 v133, v133, v200
	v_exp_f32_e32 v217, v217
	v_add_f32_e32 v135, v135, v201
	v_exp_f32_e32 v218, v218
	v_add_f32_e32 v133, v133, v202
	v_mfma_f32_32x32x16_bf16 v[48:63], v[176:179], v[90:93], v[48:63]
	v_exp_f32_e32 v219, v219
	v_add_f32_e32 v135, v135, v203
	v_exp_f32_e32 v220, v220
	v_add_f32_e32 v133, v133, v204
	v_exp_f32_e32 v221, v221
	v_add_f32_e32 v135, v135, v205
	v_mfma_f32_32x32x16_bf16 v[32:47], v[180:183], v[94:97], v[32:47]
	v_add_f32_e32 v133, v133, v206
	v_add_f32_e32 v135, v135, v207
	v_add_f32_e32 v133, v133, v208
	v_add_f32_e32 v135, v135, v209
	v_add_f32_e32 v133, v133, v210
	v_mfma_f32_32x32x16_bf16 v[48:63], v[184:187], v[94:97], v[48:63]
	v_add_f32_e32 v135, v135, v211
	v_add_f32_e32 v133, v133, v212
	v_add_f32_e32 v135, v135, v213
	v_add_f32_e32 v133, v133, v214
	v_add_f32_e32 v135, v135, v215
	v_mfma_f32_32x32x16_bf16 v[32:47], v[64:67], v[98:101], v[32:47]
	v_add_f32_e32 v133, v133, v216
	v_add_f32_e32 v135, v135, v217
	v_add_f32_e32 v133, v133, v218
	v_add_f32_e32 v135, v135, v219
	v_add_f32_e32 v133, v133, v220
	v_add_f32_e32 v135, v135, v221
	v_mfma_f32_32x32x16_bf16 v[48:63], v[68:71], v[98:101], v[48:63]
	v_cvt_pk_bf16_f32 v190, v190, v191
	v_cvt_pk_bf16_f32 v191, v192, v193
	v_cvt_pk_bf16_f32 v192, v194, v195
	v_cvt_pk_bf16_f32 v193, v196, v197
	v_cvt_pk_bf16_f32 v194, v198, v199
	v_mfma_f32_32x32x16_bf16 v[32:47], v[72:75], v[102:105], v[32:47]
	v_cvt_pk_bf16_f32 v195, v200, v201
	v_cvt_pk_bf16_f32 v196, v202, v203
	v_cvt_pk_bf16_f32 v197, v204, v205
	v_cvt_pk_bf16_f32 v206, v206, v207
	v_cvt_pk_bf16_f32 v207, v208, v209
	v_mfma_f32_32x32x16_bf16 v[48:63], v[76:79], v[102:105], v[48:63]
	v_cvt_pk_bf16_f32 v208, v210, v211
	v_cvt_pk_bf16_f32 v209, v212, v213
	v_cvt_pk_bf16_f32 v210, v214, v215
	v_cvt_pk_bf16_f32 v211, v216, v217
	v_cvt_pk_bf16_f32 v212, v218, v219
	v_cvt_pk_bf16_f32 v213, v220, v221
	s_waitcnt lgkmcnt(0)
	s_waitcnt vmcnt(3)
	s_barrier
	ds_read_b128 v[156:159], v146 offset:0
	ds_read_b128 v[160:163], v146 offset:8192
	ds_read_b128 v[164:167], v147 offset:0
	ds_read_b128 v[168:171], v147 offset:8192
	ds_read_b128 v[172:175], v148 offset:0
	ds_read_b128 v[176:179], v148 offset:8192
	ds_read_b128 v[180:183], v149 offset:0
	ds_read_b128 v[184:187], v149 offset:8192
	ds_read_b128 v[64:67], v150 offset:0
	ds_read_b128 v[68:71], v150 offset:8192
	ds_read_b128 v[72:75], v151 offset:0
	ds_read_b128 v[76:79], v151 offset:8192
	v_mfma_f32_32x32x16_bf16 v[0:15], v[190:193], v[222:225], v[0:15]
	s_add_i32 m0, s60, 0x8000
	v_exp_f32_e32 v32, v32
	v_exp_f32_e32 v33, v33
	v_mfma_f32_32x32x16_bf16 v[0:15], v[194:197], v[226:229], v[0:15]
	global_load_lds_dwordx4 v124, s[56:57]
	global_load_lds_dwordx4 v126, s[56:57] offset:1024
	v_exp_f32_e32 v34, v34
	v_exp_f32_e32 v35, v35
	v_mfma_f32_32x32x16_bf16 v[0:15], v[206:209], v[230:233], v[0:15]
	s_add_u32 s56, s56, 0x4000
	s_addc_u32 s57, s57, 0
	v_exp_f32_e32 v36, v36
	v_exp_f32_e32 v37, v37
	v_mfma_f32_32x32x16_bf16 v[0:15], v[210:213], v[234:237], v[0:15]
	s_add_i32 m0, s60, 0x10000
	v_exp_f32_e32 v38, v38
	v_exp_f32_e32 v39, v39
	v_mfma_f32_32x32x16_bf16 v[16:31], v[190:193], v[238:241], v[16:31]
	global_load_lds_dwordx4 v128, s[58:59]
	v_exp_f32_e32 v40, v40
	v_exp_f32_e32 v41, v41
	v_mfma_f32_32x32x16_bf16 v[16:31], v[194:197], v[242:245], v[16:31]
	s_add_u32 s58, s58, 0x2000
	s_addc_u32 s59, s59, 0
	v_exp_f32_e32 v42, v42
	v_exp_f32_e32 v43, v43
	v_mfma_f32_32x32x16_bf16 v[16:31], v[206:209], v[246:249], v[16:31]
	v_exp_f32_e32 v44, v44
	v_exp_f32_e32 v45, v45
	v_mfma_f32_32x32x16_bf16 v[16:31], v[210:213], v[140:143], v[16:31]
	v_exp_f32_e32 v46, v46
	v_exp_f32_e32 v47, v47
	s_waitcnt lgkmcnt(0)
; #define SBAR() __builtin_amdgcn_sched_barrier(0)
; #define ROT() do { const int t_ = bv; bv = bk; bk = bw; bw = t_; } while (0)
; __device__ __forceinline__ void partialSM(f32x16& p0) {
; #pragma unroll
;   for (int r = 0; r < 16; ++r) p0[r] = __builtin_amdgcn_exp2f(p0[r]);
; }
; __device__ __forceinline__ void finishSM(f32x16& p0, f32x16& p1, float& l_reg, bf16x8& pa0, bf16x8& pa1, bf16x8& pa2, bf16x8& pa3) {
; #pragma unroll
;   for (int r = 0; r < 16; ++r) p1[r] = __builtin_amdgcn_exp2f(p1[r]);
;   float ps = 0;
; #pragma unroll
;   for (int r = 0; r < 16; ++r) ps += p0[r];
; #pragma unroll
;   for (int r = 0; r < 16; ++r) ps += p1[r];
;   l_reg += ps;
;     ...
;   PK4(p0, 0, pa0); PK4(p0, 8, pa1); PK4(p1, 0, pa2); PK4(p1, 8, pa3);
;     ...
; }
; template <int ND> __device__ __forceinline__ void qkt(f32x16& p0, f32x16& p1, const bf16* Ks, const bf16x8* qr, int r32, int hi) {
;   p0 = f32x16{}; p1 = f32x16{};
; #pragma unroll
;   for (int d0 = 0; d0 < ND; ++d0) { int cb = (d0 * 16 + hi * 8) * 2;
;     bf16x8 b0 = *reinterpret_cast<const bf16x8*>((const char*)Ks + KSWZ(r32, cb));
;     bf16x8 b1 = *reinterpret_cast<const bf16x8*>((const char*)Ks + KSWZ(32 + r32, cb));
;     p0 = __builtin_amdgcn_mfma_f32_32x32x16_bf16(b0, qr[d0], p0, 0, 0, 0);
;     p1 = __builtin_amdgcn_mfma_f32_32x32x16_bf16(b1, qr[d0], p1, 0, 0, 0); }
; }
; template <bool SHIFT> __device__ __forceinline__ void attn_dense_body(const bf16* __restrict__ Qb, const bf16* __restrict__ Kh, const bf16* __restrict__ Vh, bf16* __restrict__ Ob, int seq, char* lds, LAS unsigned char* ldsl, float negB, const float* __restrict__ gq, int qpos0) {
;     ...
;   for (int j = 1; j + 1 < NT; j += 2) {
;     DMA(bw, (j + 1) * KVBLK);
;     SBAR(); qkt<SHIFT ? 7 : 6>(pB0, pB1, (bf16*)((char*)K_lds + bk * SHM_K), qr, r32, hi);
;     finishSM(pA0, pA1, l_reg, pa0, pa1, pa2, pa3); SBAR();
;     pv_d0(o, vb0 + bv * (int)SHM_V, pa0, pa1, pa2, pa3); partialSM(pB0);
;     asm volatile("s_waitcnt vmcnt(0)" ::: "memory"); __syncthreads(); ROT();
;     DMA(bw, (j + 2) * KVBLK);
;     SBAR(); qkt<SHIFT ? 7 : 6>(pA0, pA1, (bf16*)((char*)K_lds + bk * SHM_K), qr, r32, hi);
;     finishSM(pB0, pB1, l_reg, pa0, pa1, pa2, pa3); SBAR();
;     pv_d0(o, vb0 + bv * (int)SHM_V, pa0, pa1, pa2, pa3); partialSM(pA0);
;     asm volatile("s_waitcnt vmcnt(0)" ::: "memory"); __syncthreads(); ROT();
;   }
	ds_read_b64_tr_b16 v[222:223], v134 offset:32768
	ds_read_b64_tr_b16 v[224:225], v134 offset:34816
	ds_read_b64_tr_b16 v[226:227], v134 offset:36864
	ds_read_b64_tr_b16 v[228:229], v134 offset:38912
	ds_read_b64_tr_b16 v[230:231], v134 offset:40960
	ds_read_b64_tr_b16 v[232:233], v134 offset:43008
	ds_read_b64_tr_b16 v[234:235], v134 offset:45056
	ds_read_b64_tr_b16 v[236:237], v134 offset:47104
	v_mfma_f32_32x32x16_bf16 v[190:205], v[156:159], v[86:89], 0
	v_exp_f32_e32 v48, v48
	v_add_f32_e32 v133, v133, v32
	v_exp_f32_e32 v49, v49
	v_add_f32_e32 v135, v135, v33
	v_exp_f32_e32 v50, v50
	v_mfma_f32_32x32x16_bf16 v[206:221], v[160:163], v[86:89], 0
	v_add_f32_e32 v133, v133, v34
	v_exp_f32_e32 v51, v51
	v_add_f32_e32 v135, v135, v35
	v_exp_f32_e32 v52, v52
	v_add_f32_e32 v133, v133, v36
	v_mfma_f32_32x32x16_bf16 v[190:205], v[164:167], v[82:85], v[190:205]
	v_exp_f32_e32 v53, v53
	v_add_f32_e32 v135, v135, v37
	v_exp_f32_e32 v54, v54
	v_add_f32_e32 v133, v133, v38
	v_exp_f32_e32 v55, v55
	v_add_f32_e32 v135, v135, v39
	v_mfma_f32_32x32x16_bf16 v[206:221], v[168:171], v[82:85], v[206:221]
	s_waitcnt lgkmcnt(7)
	ds_read_b64_tr_b16 v[238:239], v134 offset:33280
	ds_read_b64_tr_b16 v[240:241], v134 offset:35328
	ds_read_b64_tr_b16 v[242:243], v134 offset:37376
	ds_read_b64_tr_b16 v[244:245], v134 offset:39424
	ds_read_b64_tr_b16 v[246:247], v134 offset:41472
	ds_read_b64_tr_b16 v[248:249], v134 offset:43520
	ds_read_b64_tr_b16 v[140:141], v134 offset:45568
	ds_read_b64_tr_b16 v[142:143], v134 offset:47616
	v_exp_f32_e32 v56, v56
	v_add_f32_e32 v133, v133, v40
	v_exp_f32_e32 v57, v57
	v_add_f32_e32 v135, v135, v41
	v_exp_f32_e32 v58, v58
	v_mfma_f32_32x32x16_bf16 v[190:205], v[172:175], v[90:93], v[190:205]
	v_add_f32_e32 v133, v133, v42
	v_exp_f32_e32 v59, v59
	v_add_f32_e32 v135, v135, v43
	v_exp_f32_e32 v60, v60
	v_add_f32_e32 v133, v133, v44
	v_mfma_f32_32x32x16_bf16 v[206:221], v[176:179], v[90:93], v[206:221]
	v_exp_f32_e32 v61, v61
	v_add_f32_e32 v135, v135, v45
	v_exp_f32_e32 v62, v62
	v_add_f32_e32 v133, v133, v46
	v_exp_f32_e32 v63, v63
	v_add_f32_e32 v135, v135, v47
	v_mfma_f32_32x32x16_bf16 v[190:205], v[180:183], v[94:97], v[190:205]
	v_add_f32_e32 v133, v133, v48
	v_add_f32_e32 v135, v135, v49
	v_add_f32_e32 v133, v133, v50
	v_add_f32_e32 v135, v135, v51
	v_add_f32_e32 v133, v133, v52
	v_mfma_f32_32x32x16_bf16 v[206:221], v[184:187], v[94:97], v[206:221]
	v_add_f32_e32 v135, v135, v53
	v_add_f32_e32 v133, v133, v54
	v_add_f32_e32 v135, v135, v55
	v_add_f32_e32 v133, v133, v56
	v_add_f32_e32 v135, v135, v57
	v_mfma_f32_32x32x16_bf16 v[190:205], v[64:67], v[98:101], v[190:205]
	v_add_f32_e32 v133, v133, v58
	v_add_f32_e32 v135, v135, v59
	v_add_f32_e32 v133, v133, v60
	v_add_f32_e32 v135, v135, v61
	v_add_f32_e32 v133, v133, v62
	v_add_f32_e32 v135, v135, v63
	v_mfma_f32_32x32x16_bf16 v[206:221], v[68:71], v[98:101], v[206:221]
	v_cvt_pk_bf16_f32 v32, v32, v33
	v_cvt_pk_bf16_f32 v33, v34, v35
	v_cvt_pk_bf16_f32 v34, v36, v37
	v_cvt_pk_bf16_f32 v35, v38, v39
	v_cvt_pk_bf16_f32 v36, v40, v41
	v_mfma_f32_32x32x16_bf16 v[190:205], v[72:75], v[102:105], v[190:205]
	v_cvt_pk_bf16_f32 v37, v42, v43
	v_cvt_pk_bf16_f32 v38, v44, v45
	v_cvt_pk_bf16_f32 v39, v46, v47
	v_cvt_pk_bf16_f32 v48, v48, v49
	v_cvt_pk_bf16_f32 v49, v50, v51
	v_mfma_f32_32x32x16_bf16 v[206:221], v[76:79], v[102:105], v[206:221]
	v_cvt_pk_bf16_f32 v50, v52, v53
	v_cvt_pk_bf16_f32 v51, v54, v55
	v_cvt_pk_bf16_f32 v52, v56, v57
	v_cvt_pk_bf16_f32 v53, v58, v59
	v_cvt_pk_bf16_f32 v54, v60, v61
	v_cvt_pk_bf16_f32 v55, v62, v63
	s_waitcnt lgkmcnt(0)
	s_waitcnt vmcnt(3)
	s_barrier
	ds_read_b128 v[156:159], v146 offset:16384
	ds_read_b128 v[160:163], v146 offset:24576
	ds_read_b128 v[164:167], v147 offset:16384
	ds_read_b128 v[168:171], v147 offset:24576
	ds_read_b128 v[172:175], v148 offset:16384
	ds_read_b128 v[176:179], v148 offset:24576
	ds_read_b128 v[180:183], v149 offset:16384
	ds_read_b128 v[184:187], v149 offset:24576
	ds_read_b128 v[64:67], v150 offset:16384
	ds_read_b128 v[68:71], v150 offset:24576
	ds_read_b128 v[72:75], v151 offset:16384
	ds_read_b128 v[76:79], v151 offset:24576
	v_mfma_f32_32x32x16_bf16 v[0:15], v[32:35], v[222:225], v[0:15]
	s_add_i32 m0, s60, 0x0
	v_exp_f32_e32 v190, v190
	v_exp_f32_e32 v191, v191
	v_mfma_f32_32x32x16_bf16 v[0:15], v[36:39], v[226:229], v[0:15]
	global_load_lds_dwordx4 v124, s[56:57]
	global_load_lds_dwordx4 v126, s[56:57] offset:1024
	v_exp_f32_e32 v192, v192
	v_exp_f32_e32 v193, v193
	v_mfma_f32_32x32x16_bf16 v[0:15], v[48:51], v[230:233], v[0:15]
	s_add_u32 s56, s56, 0x4000
	s_addc_u32 s57, s57, 0
	v_exp_f32_e32 v194, v194
	v_exp_f32_e32 v195, v195
	v_mfma_f32_32x32x16_bf16 v[0:15], v[52:55], v[234:237], v[0:15]
	s_add_i32 m0, s60, 0x14000
	v_exp_f32_e32 v196, v196
	v_exp_f32_e32 v197, v197
	v_mfma_f32_32x32x16_bf16 v[16:31], v[32:35], v[238:241], v[16:31]
	global_load_lds_dwordx4 v128, s[58:59]
	v_exp_f32_e32 v198, v198
	v_exp_f32_e32 v199, v199
	v_mfma_f32_32x32x16_bf16 v[16:31], v[36:39], v[242:245], v[16:31]
	s_add_u32 s58, s58, 0x2000
	s_addc_u32 s59, s59, 0
	v_exp_f32_e32 v200, v200
	v_exp_f32_e32 v201, v201
	v_mfma_f32_32x32x16_bf16 v[16:31], v[48:51], v[246:249], v[16:31]
	v_exp_f32_e32 v202, v202
	v_exp_f32_e32 v203, v203
	v_mfma_f32_32x32x16_bf16 v[16:31], v[52:55], v[140:143], v[16:31]
	v_exp_f32_e32 v204, v204
	v_exp_f32_e32 v205, v205
	s_waitcnt lgkmcnt(0)
; #define SBAR() __builtin_amdgcn_sched_barrier(0)
; #define ROT() do { const int t_ = bv; bv = bk; bk = bw; bw = t_; } while (0)
; __device__ __forceinline__ void partialSM(f32x16& p0) {
; #pragma unroll
;   for (int r = 0; r < 16; ++r) p0[r] = __builtin_amdgcn_exp2f(p0[r]);
; }
; __device__ __forceinline__ void finishSM(f32x16& p0, f32x16& p1, float& l_reg, bf16x8& pa0, bf16x8& pa1, bf16x8& pa2, bf16x8& pa3) {
; #pragma unroll
;   for (int r = 0; r < 16; ++r) p1[r] = __builtin_amdgcn_exp2f(p1[r]);
;   float ps = 0;
; #pragma unroll
;   for (int r = 0; r < 16; ++r) ps += p0[r];
; #pragma unroll
;   for (int r = 0; r < 16; ++r) ps += p1[r];
;   l_reg += ps;
;     ...
;   PK4(p0, 0, pa0); PK4(p0, 8, pa1); PK4(p1, 0, pa2); PK4(p1, 8, pa3);
;     ...
; }
; template <int ND> __device__ __forceinline__ void qkt(f32x16& p0, f32x16& p1, const bf16* Ks, const bf16x8* qr, int r32, int hi) {
;   p0 = f32x16{}; p1 = f32x16{};
; #pragma unroll
;   for (int d0 = 0; d0 < ND; ++d0) { int cb = (d0 * 16 + hi * 8) * 2;
;     bf16x8 b0 = *reinterpret_cast<const bf16x8*>((const char*)Ks + KSWZ(r32, cb));
;     bf16x8 b1 = *reinterpret_cast<const bf16x8*>((const char*)Ks + KSWZ(32 + r32, cb));
;     p0 = __builtin_amdgcn_mfma_f32_32x32x16_bf16(b0, qr[d0], p0, 0, 0, 0);
;     p1 = __builtin_amdgcn_mfma_f32_32x32x16_bf16(b1, qr[d0], p1, 0, 0, 0); }
; }
; template <bool SHIFT> __device__ __forceinline__ void attn_dense_body(const bf16* __restrict__ Qb, const bf16* __restrict__ Kh, const bf16* __restrict__ Vh, bf16* __restrict__ Ob, int seq, char* lds, LAS unsigned char* ldsl, float negB, const float* __restrict__ gq, int qpos0) {
;     ...
;   for (int j = 1; j + 1 < NT; j += 2) {
;     DMA(bw, (j + 1) * KVBLK);
;     SBAR(); qkt<SHIFT ? 7 : 6>(pB0, pB1, (bf16*)((char*)K_lds + bk * SHM_K), qr, r32, hi);
;     finishSM(pA0, pA1, l_reg, pa0, pa1, pa2, pa3); SBAR();
;     pv_d0(o, vb0 + bv * (int)SHM_V, pa0, pa1, pa2, pa3); partialSM(pB0);
;     asm volatile("s_waitcnt vmcnt(0)" ::: "memory"); __syncthreads(); ROT();
;     DMA(bw, (j + 2) * KVBLK);
;     SBAR(); qkt<SHIFT ? 7 : 6>(pA0, pA1, (bf16*)((char*)K_lds + bk * SHM_K), qr, r32, hi);
;     finishSM(pB0, pB1, l_reg, pa0, pa1, pa2, pa3); SBAR();
;     pv_d0(o, vb0 + bv * (int)SHM_V, pa0, pa1, pa2, pa3); partialSM(pA0);
;     asm volatile("s_waitcnt vmcnt(0)" ::: "memory"); __syncthreads(); ROT();
;   }
	ds_read_b64_tr_b16 v[222:223], v134 offset:0
	ds_read_b64_tr_b16 v[224:225], v134 offset:2048
	ds_read_b64_tr_b16 v[226:227], v134 offset:4096
	ds_read_b64_tr_b16 v[228:229], v134 offset:6144
	ds_read_b64_tr_b16 v[230:231], v134 offset:8192
	ds_read_b64_tr_b16 v[232:233], v134 offset:10240
	ds_read_b64_tr_b16 v[234:235], v134 offset:12288
	ds_read_b64_tr_b16 v[236:237], v134 offset:14336
	v_mfma_f32_32x32x16_bf16 v[32:47], v[156:159], v[86:89], 0
	v_exp_f32_e32 v206, v206
	v_add_f32_e32 v133, v133, v190
	v_exp_f32_e32 v207, v207
	v_add_f32_e32 v135, v135, v191
	v_exp_f32_e32 v208, v208
	v_mfma_f32_32x32x16_bf16 v[48:63], v[160:163], v[86:89], 0
	v_add_f32_e32 v133, v133, v192
	v_exp_f32_e32 v209, v209
	v_add_f32_e32 v135, v135, v193
	v_exp_f32_e32 v210, v210
	v_add_f32_e32 v133, v133, v194
	v_mfma_f32_32x32x16_bf16 v[32:47], v[164:167], v[82:85], v[32:47]
	v_exp_f32_e32 v211, v211
	v_add_f32_e32 v135, v135, v195
	v_exp_f32_e32 v212, v212
	v_add_f32_e32 v133, v133, v196
	v_exp_f32_e32 v213, v213
	v_add_f32_e32 v135, v135, v197
	v_mfma_f32_32x32x16_bf16 v[48:63], v[168:171], v[82:85], v[48:63]
	s_waitcnt lgkmcnt(7)
	ds_read_b64_tr_b16 v[238:239], v134 offset:512
	ds_read_b64_tr_b16 v[240:241], v134 offset:2560
	ds_read_b64_tr_b16 v[242:243], v134 offset:4608
	ds_read_b64_tr_b16 v[244:245], v134 offset:6656
	ds_read_b64_tr_b16 v[246:247], v134 offset:8704
	ds_read_b64_tr_b16 v[248:249], v134 offset:10752
	ds_read_b64_tr_b16 v[140:141], v134 offset:12800
	ds_read_b64_tr_b16 v[142:143], v134 offset:14848
	v_exp_f32_e32 v214, v214
	v_add_f32_e32 v133, v133, v198
	v_exp_f32_e32 v215, v215
	v_add_f32_e32 v135, v135, v199
	v_exp_f32_e32 v216, v216
	v_mfma_f32_32x32x16_bf16 v[32:47], v[172:175], v[90:93], v[32:47]
	v_add_f32_e32 v133, v133, v200
	v_exp_f32_e32 v217, v217
	v_add_f32_e32 v135, v135, v201
	v_exp_f32_e32 v218, v218
	v_add_f32_e32 v133, v133, v202
	v_mfma_f32_32x32x16_bf16 v[48:63], v[176:179], v[90:93], v[48:63]
	v_exp_f32_e32 v219, v219
	v_add_f32_e32 v135, v135, v203
	v_exp_f32_e32 v220, v220
	v_add_f32_e32 v133, v133, v204
	v_exp_f32_e32 v221, v221
	v_add_f32_e32 v135, v135, v205
	v_mfma_f32_32x32x16_bf16 v[32:47], v[180:183], v[94:97], v[32:47]
	v_add_f32_e32 v133, v133, v206
	v_add_f32_e32 v135, v135, v207
	v_add_f32_e32 v133, v133, v208
	v_add_f32_e32 v135, v135, v209
	v_add_f32_e32 v133, v133, v210
	v_mfma_f32_32x32x16_bf16 v[48:63], v[184:187], v[94:97], v[48:63]
	v_add_f32_e32 v135, v135, v211
	v_add_f32_e32 v133, v133, v212
	v_add_f32_e32 v135, v135, v213
	v_add_f32_e32 v133, v133, v214
	v_add_f32_e32 v135, v135, v215
	v_mfma_f32_32x32x16_bf16 v[32:47], v[64:67], v[98:101], v[32:47]
	v_add_f32_e32 v133, v133, v216
	v_add_f32_e32 v135, v135, v217
	v_add_f32_e32 v133, v133, v218
	v_add_f32_e32 v135, v135, v219
	v_add_f32_e32 v133, v133, v220
	v_add_f32_e32 v135, v135, v221
	v_mfma_f32_32x32x16_bf16 v[48:63], v[68:71], v[98:101], v[48:63]
	v_cvt_pk_bf16_f32 v190, v190, v191
	v_cvt_pk_bf16_f32 v191, v192, v193
	v_cvt_pk_bf16_f32 v192, v194, v195
	v_cvt_pk_bf16_f32 v193, v196, v197
	v_cvt_pk_bf16_f32 v194, v198, v199
	v_mfma_f32_32x32x16_bf16 v[32:47], v[72:75], v[102:105], v[32:47]
	v_cvt_pk_bf16_f32 v195, v200, v201
	v_cvt_pk_bf16_f32 v196, v202, v203
	v_cvt_pk_bf16_f32 v197, v204, v205
	v_cvt_pk_bf16_f32 v206, v206, v207
	v_cvt_pk_bf16_f32 v207, v208, v209
	v_mfma_f32_32x32x16_bf16 v[48:63], v[76:79], v[102:105], v[48:63]
	v_cvt_pk_bf16_f32 v208, v210, v211
	v_cvt_pk_bf16_f32 v209, v212, v213
	v_cvt_pk_bf16_f32 v210, v214, v215
	v_cvt_pk_bf16_f32 v211, v216, v217
	v_cvt_pk_bf16_f32 v212, v218, v219
	v_cvt_pk_bf16_f32 v213, v220, v221
	s_waitcnt lgkmcnt(0)
	s_waitcnt vmcnt(3)
	s_barrier
	ds_read_b128 v[156:159], v146 offset:32768
	ds_read_b128 v[160:163], v146 offset:40960
	ds_read_b128 v[164:167], v147 offset:32768
	ds_read_b128 v[168:171], v147 offset:40960
	ds_read_b128 v[172:175], v148 offset:32768
	ds_read_b128 v[176:179], v148 offset:40960
	ds_read_b128 v[180:183], v149 offset:32768
	ds_read_b128 v[184:187], v149 offset:40960
	ds_read_b128 v[64:67], v150 offset:32768
	ds_read_b128 v[68:71], v150 offset:40960
	ds_read_b128 v[72:75], v151 offset:32768
	ds_read_b128 v[76:79], v151 offset:40960
	v_mfma_f32_32x32x16_bf16 v[0:15], v[190:193], v[222:225], v[0:15]
	s_add_i32 m0, s60, 0x4000
	v_exp_f32_e32 v32, v32
	v_exp_f32_e32 v33, v33
	v_mfma_f32_32x32x16_bf16 v[0:15], v[194:197], v[226:229], v[0:15]
	global_load_lds_dwordx4 v124, s[56:57]
	global_load_lds_dwordx4 v126, s[56:57] offset:1024
	v_exp_f32_e32 v34, v34
	v_exp_f32_e32 v35, v35
	v_mfma_f32_32x32x16_bf16 v[0:15], v[206:209], v[230:233], v[0:15]
	s_add_u32 s56, s56, 0x4000
	s_addc_u32 s57, s57, 0
	v_exp_f32_e32 v36, v36
	v_exp_f32_e32 v37, v37
	v_mfma_f32_32x32x16_bf16 v[0:15], v[210:213], v[234:237], v[0:15]
	s_add_i32 m0, s60, 0xc000
	v_exp_f32_e32 v38, v38
	v_exp_f32_e32 v39, v39
	v_mfma_f32_32x32x16_bf16 v[16:31], v[190:193], v[238:241], v[16:31]
	global_load_lds_dwordx4 v128, s[58:59]
	v_exp_f32_e32 v40, v40
	v_exp_f32_e32 v41, v41
	v_mfma_f32_32x32x16_bf16 v[16:31], v[194:197], v[242:245], v[16:31]
	s_add_u32 s58, s58, 0x2000
	s_addc_u32 s59, s59, 0
	v_exp_f32_e32 v42, v42
	v_exp_f32_e32 v43, v43
	v_mfma_f32_32x32x16_bf16 v[16:31], v[206:209], v[246:249], v[16:31]
	v_exp_f32_e32 v44, v44
	v_exp_f32_e32 v45, v45
	v_mfma_f32_32x32x16_bf16 v[16:31], v[210:213], v[140:143], v[16:31]
	v_exp_f32_e32 v46, v46
	v_exp_f32_e32 v47, v47
	s_waitcnt lgkmcnt(0)
; #define SBAR() __builtin_amdgcn_sched_barrier(0)
; #define ROT() do { const int t_ = bv; bv = bk; bk = bw; bw = t_; } while (0)
; __device__ __forceinline__ void partialSM(f32x16& p0) {
; #pragma unroll
;   for (int r = 0; r < 16; ++r) p0[r] = __builtin_amdgcn_exp2f(p0[r]);
; }
; __device__ __forceinline__ void finishSM(f32x16& p0, f32x16& p1, float& l_reg, bf16x8& pa0, bf16x8& pa1, bf16x8& pa2, bf16x8& pa3) {
; #pragma unroll
;   for (int r = 0; r < 16; ++r) p1[r] = __builtin_amdgcn_exp2f(p1[r]);
;   float ps = 0;
; #pragma unroll
;   for (int r = 0; r < 16; ++r) ps += p0[r];
; #pragma unroll
;   for (int r = 0; r < 16; ++r) ps += p1[r];
;   l_reg += ps;
;     ...
;   PK4(p0, 0, pa0); PK4(p0, 8, pa1); PK4(p1, 0, pa2); PK4(p1, 8, pa3);
;     ...
; }
; template <int ND> __device__ __forceinline__ void qkt(f32x16& p0, f32x16& p1, const bf16* Ks, const bf16x8* qr, int r32, int hi) {
;   p0 = f32x16{}; p1 = f32x16{};
; #pragma unroll
;   for (int d0 = 0; d0 < ND; ++d0) { int cb = (d0 * 16 + hi * 8) * 2;
;     bf16x8 b0 = *reinterpret_cast<const bf16x8*>((const char*)Ks + KSWZ(r32, cb));
;     bf16x8 b1 = *reinterpret_cast<const bf16x8*>((const char*)Ks + KSWZ(32 + r32, cb));
;     p0 = __builtin_amdgcn_mfma_f32_32x32x16_bf16(b0, qr[d0], p0, 0, 0, 0);
;     p1 = __builtin_amdgcn_mfma_f32_32x32x16_bf16(b1, qr[d0], p1, 0, 0, 0); }
; }
; template <bool SHIFT> __device__ __forceinline__ void attn_dense_body(const bf16* __restrict__ Qb, const bf16* __restrict__ Kh, const bf16* __restrict__ Vh, bf16* __restrict__ Ob, int seq, char* lds, LAS unsigned char* ldsl, float negB, const float* __restrict__ gq, int qpos0) {
;     ...
;   for (int j = 1; j + 1 < NT; j += 2) {
;     DMA(bw, (j + 1) * KVBLK);
;     SBAR(); qkt<SHIFT ? 7 : 6>(pB0, pB1, (bf16*)((char*)K_lds + bk * SHM_K), qr, r32, hi);
;     finishSM(pA0, pA1, l_reg, pa0, pa1, pa2, pa3); SBAR();
;     pv_d0(o, vb0 + bv * (int)SHM_V, pa0, pa1, pa2, pa3); partialSM(pB0);
;     asm volatile("s_waitcnt vmcnt(0)" ::: "memory"); __syncthreads(); ROT();
;     DMA(bw, (j + 2) * KVBLK);
;     SBAR(); qkt<SHIFT ? 7 : 6>(pA0, pA1, (bf16*)((char*)K_lds + bk * SHM_K), qr, r32, hi);
;     finishSM(pB0, pB1, l_reg, pa0, pa1, pa2, pa3); SBAR();
;     pv_d0(o, vb0 + bv * (int)SHM_V, pa0, pa1, pa2, pa3); partialSM(pA0);
;     asm volatile("s_waitcnt vmcnt(0)" ::: "memory"); __syncthreads(); ROT();
;   }
	ds_read_b64_tr_b16 v[222:223], v134 offset:16384
	ds_read_b64_tr_b16 v[224:225], v134 offset:18432
	ds_read_b64_tr_b16 v[226:227], v134 offset:20480
	ds_read_b64_tr_b16 v[228:229], v134 offset:22528
	ds_read_b64_tr_b16 v[230:231], v134 offset:24576
	ds_read_b64_tr_b16 v[232:233], v134 offset:26624
	ds_read_b64_tr_b16 v[234:235], v134 offset:28672
	ds_read_b64_tr_b16 v[236:237], v134 offset:30720
	v_mfma_f32_32x32x16_bf16 v[190:205], v[156:159], v[86:89], 0
	v_exp_f32_e32 v48, v48
	v_add_f32_e32 v133, v133, v32
	v_exp_f32_e32 v49, v49
	v_add_f32_e32 v135, v135, v33
	v_exp_f32_e32 v50, v50
	v_mfma_f32_32x32x16_bf16 v[206:221], v[160:163], v[86:89], 0
	v_add_f32_e32 v133, v133, v34
	v_exp_f32_e32 v51, v51
	v_add_f32_e32 v135, v135, v35
	v_exp_f32_e32 v52, v52
	v_add_f32_e32 v133, v133, v36
	v_mfma_f32_32x32x16_bf16 v[190:205], v[164:167], v[82:85], v[190:205]
	v_exp_f32_e32 v53, v53
	v_add_f32_e32 v135, v135, v37
	v_exp_f32_e32 v54, v54
	v_add_f32_e32 v133, v133, v38
	v_exp_f32_e32 v55, v55
	v_add_f32_e32 v135, v135, v39
	v_mfma_f32_32x32x16_bf16 v[206:221], v[168:171], v[82:85], v[206:221]
	s_waitcnt lgkmcnt(7)
	ds_read_b64_tr_b16 v[238:239], v134 offset:16896
	ds_read_b64_tr_b16 v[240:241], v134 offset:18944
	ds_read_b64_tr_b16 v[242:243], v134 offset:20992
	ds_read_b64_tr_b16 v[244:245], v134 offset:23040
	ds_read_b64_tr_b16 v[246:247], v134 offset:25088
	ds_read_b64_tr_b16 v[248:249], v134 offset:27136
	ds_read_b64_tr_b16 v[140:141], v134 offset:29184
	ds_read_b64_tr_b16 v[142:143], v134 offset:31232
	v_exp_f32_e32 v56, v56
	v_add_f32_e32 v133, v133, v40
	v_exp_f32_e32 v57, v57
	v_add_f32_e32 v135, v135, v41
	v_exp_f32_e32 v58, v58
	v_mfma_f32_32x32x16_bf16 v[190:205], v[172:175], v[90:93], v[190:205]
	v_add_f32_e32 v133, v133, v42
	v_exp_f32_e32 v59, v59
	v_add_f32_e32 v135, v135, v43
	v_exp_f32_e32 v60, v60
	v_add_f32_e32 v133, v133, v44
	v_mfma_f32_32x32x16_bf16 v[206:221], v[176:179], v[90:93], v[206:221]
	v_exp_f32_e32 v61, v61
	v_add_f32_e32 v135, v135, v45
	v_exp_f32_e32 v62, v62
	v_add_f32_e32 v133, v133, v46
	v_exp_f32_e32 v63, v63
	v_add_f32_e32 v135, v135, v47
	v_mfma_f32_32x32x16_bf16 v[190:205], v[180:183], v[94:97], v[190:205]
	v_add_f32_e32 v133, v133, v48
	v_add_f32_e32 v135, v135, v49
	v_add_f32_e32 v133, v133, v50
	v_add_f32_e32 v135, v135, v51
	v_add_f32_e32 v133, v133, v52
	v_mfma_f32_32x32x16_bf16 v[206:221], v[184:187], v[94:97], v[206:221]
	v_add_f32_e32 v135, v135, v53
	v_add_f32_e32 v133, v133, v54
	v_add_f32_e32 v135, v135, v55
	v_add_f32_e32 v133, v133, v56
	v_add_f32_e32 v135, v135, v57
	v_mfma_f32_32x32x16_bf16 v[190:205], v[64:67], v[98:101], v[190:205]
	v_add_f32_e32 v133, v133, v58
	v_add_f32_e32 v135, v135, v59
	v_add_f32_e32 v133, v133, v60
	v_add_f32_e32 v135, v135, v61
	v_add_f32_e32 v133, v133, v62
	v_add_f32_e32 v135, v135, v63
	v_mfma_f32_32x32x16_bf16 v[206:221], v[68:71], v[98:101], v[206:221]
	v_cvt_pk_bf16_f32 v32, v32, v33
	v_cvt_pk_bf16_f32 v33, v34, v35
	v_cvt_pk_bf16_f32 v34, v36, v37
	v_cvt_pk_bf16_f32 v35, v38, v39
	v_cvt_pk_bf16_f32 v36, v40, v41
	v_mfma_f32_32x32x16_bf16 v[190:205], v[72:75], v[102:105], v[190:205]
	v_cvt_pk_bf16_f32 v37, v42, v43
	v_cvt_pk_bf16_f32 v38, v44, v45
	v_cvt_pk_bf16_f32 v39, v46, v47
	v_cvt_pk_bf16_f32 v48, v48, v49
	v_cvt_pk_bf16_f32 v49, v50, v51
	v_mfma_f32_32x32x16_bf16 v[206:221], v[76:79], v[102:105], v[206:221]
	v_cvt_pk_bf16_f32 v50, v52, v53
	v_cvt_pk_bf16_f32 v51, v54, v55
	v_cvt_pk_bf16_f32 v52, v56, v57
	v_cvt_pk_bf16_f32 v53, v58, v59
	v_cvt_pk_bf16_f32 v54, v60, v61
	v_cvt_pk_bf16_f32 v55, v62, v63
	s_waitcnt lgkmcnt(0)
	s_waitcnt vmcnt(3)
	s_barrier
	ds_read_b128 v[156:159], v146 offset:0
	ds_read_b128 v[160:163], v146 offset:8192
	ds_read_b128 v[164:167], v147 offset:0
	ds_read_b128 v[168:171], v147 offset:8192
	ds_read_b128 v[172:175], v148 offset:0
	ds_read_b128 v[176:179], v148 offset:8192
	ds_read_b128 v[180:183], v149 offset:0
	ds_read_b128 v[184:187], v149 offset:8192
	ds_read_b128 v[64:67], v150 offset:0
	ds_read_b128 v[68:71], v150 offset:8192
	ds_read_b128 v[72:75], v151 offset:0
	ds_read_b128 v[76:79], v151 offset:8192
	v_mfma_f32_32x32x16_bf16 v[0:15], v[32:35], v[222:225], v[0:15]
	s_add_i32 m0, s60, 0x10000
	v_exp_f32_e32 v190, v190
	v_exp_f32_e32 v191, v191
	v_mfma_f32_32x32x16_bf16 v[0:15], v[36:39], v[226:229], v[0:15]
	global_load_lds_dwordx4 v128, s[58:59]
	v_exp_f32_e32 v192, v192
	v_exp_f32_e32 v193, v193
	v_mfma_f32_32x32x16_bf16 v[0:15], v[48:51], v[230:233], v[0:15]
	s_add_u32 s58, s58, 0x2000
	s_addc_u32 s59, s59, 0
	v_exp_f32_e32 v194, v194
	v_exp_f32_e32 v195, v195
	v_mfma_f32_32x32x16_bf16 v[0:15], v[52:55], v[234:237], v[0:15]
	v_exp_f32_e32 v196, v196
	v_exp_f32_e32 v197, v197
	v_mfma_f32_32x32x16_bf16 v[16:31], v[32:35], v[238:241], v[16:31]
	v_exp_f32_e32 v198, v198
	v_exp_f32_e32 v199, v199
	v_mfma_f32_32x32x16_bf16 v[16:31], v[36:39], v[242:245], v[16:31]
	v_exp_f32_e32 v200, v200
	v_exp_f32_e32 v201, v201
	v_mfma_f32_32x32x16_bf16 v[16:31], v[48:51], v[246:249], v[16:31]
	v_exp_f32_e32 v202, v202
	v_exp_f32_e32 v203, v203
	v_mfma_f32_32x32x16_bf16 v[16:31], v[52:55], v[140:143], v[16:31]
	v_exp_f32_e32 v204, v204
	v_exp_f32_e32 v205, v205
	s_waitcnt lgkmcnt(0)
; #define SBAR() __builtin_amdgcn_sched_barrier(0)
; #define ROT() do { const int t_ = bv; bv = bk; bk = bw; bw = t_; } while (0)
; __device__ __forceinline__ void partialSM(f32x16& p0) {
; #pragma unroll
;   for (int r = 0; r < 16; ++r) p0[r] = __builtin_amdgcn_exp2f(p0[r]);
; }
; __device__ __forceinline__ void finishSM(f32x16& p0, f32x16& p1, float& l_reg, bf16x8& pa0, bf16x8& pa1, bf16x8& pa2, bf16x8& pa3) {
; #pragma unroll
;   for (int r = 0; r < 16; ++r) p1[r] = __builtin_amdgcn_exp2f(p1[r]);
;   float ps = 0;
; #pragma unroll
;   for (int r = 0; r < 16; ++r) ps += p0[r];
; #pragma unroll
;   for (int r = 0; r < 16; ++r) ps += p1[r];
;   l_reg += ps;
;     ...
;   PK4(p0, 0, pa0); PK4(p0, 8, pa1); PK4(p1, 0, pa2); PK4(p1, 8, pa3);
;     ...
; }
; template <int ND> __device__ __forceinline__ void qkt(f32x16& p0, f32x16& p1, const bf16* Ks, const bf16x8* qr, int r32, int hi) {
;   p0 = f32x16{}; p1 = f32x16{};
; #pragma unroll
;   for (int d0 = 0; d0 < ND; ++d0) { int cb = (d0 * 16 + hi * 8) * 2;
;     bf16x8 b0 = *reinterpret_cast<const bf16x8*>((const char*)Ks + KSWZ(r32, cb));
;     bf16x8 b1 = *reinterpret_cast<const bf16x8*>((const char*)Ks + KSWZ(32 + r32, cb));
;     p0 = __builtin_amdgcn_mfma_f32_32x32x16_bf16(b0, qr[d0], p0, 0, 0, 0);
;     p1 = __builtin_amdgcn_mfma_f32_32x32x16_bf16(b1, qr[d0], p1, 0, 0, 0); }
; }
; template <bool SHIFT> __device__ __forceinline__ void attn_dense_body(const bf16* __restrict__ Qb, const bf16* __restrict__ Kh, const bf16* __restrict__ Vh, bf16* __restrict__ Ob, int seq, char* lds, LAS unsigned char* ldsl, float negB, const float* __restrict__ gq, int qpos0) {
;     ...
;   for (int j = 1; j + 1 < NT; j += 2) {
;     DMA(bw, (j + 1) * KVBLK);
;     SBAR(); qkt<SHIFT ? 7 : 6>(pB0, pB1, (bf16*)((char*)K_lds + bk * SHM_K), qr, r32, hi);
;     finishSM(pA0, pA1, l_reg, pa0, pa1, pa2, pa3); SBAR();
;     pv_d0(o, vb0 + bv * (int)SHM_V, pa0, pa1, pa2, pa3); partialSM(pB0);
;     asm volatile("s_waitcnt vmcnt(0)" ::: "memory"); __syncthreads(); ROT();
;     DMA(bw, (j + 2) * KVBLK);
;     SBAR(); qkt<SHIFT ? 7 : 6>(pA0, pA1, (bf16*)((char*)K_lds + bk * SHM_K), qr, r32, hi);
;     finishSM(pB0, pB1, l_reg, pa0, pa1, pa2, pa3); SBAR();
;     pv_d0(o, vb0 + bv * (int)SHM_V, pa0, pa1, pa2, pa3); partialSM(pA0);
;     asm volatile("s_waitcnt vmcnt(0)" ::: "memory"); __syncthreads(); ROT();
;   }
	ds_read_b64_tr_b16 v[222:223], v134 offset:32768
	ds_read_b64_tr_b16 v[224:225], v134 offset:34816
	ds_read_b64_tr_b16 v[226:227], v134 offset:36864
	ds_read_b64_tr_b16 v[228:229], v134 offset:38912
	ds_read_b64_tr_b16 v[230:231], v134 offset:40960
	ds_read_b64_tr_b16 v[232:233], v134 offset:43008
	ds_read_b64_tr_b16 v[234:235], v134 offset:45056
	ds_read_b64_tr_b16 v[236:237], v134 offset:47104
	v_mfma_f32_32x32x16_bf16 v[32:47], v[156:159], v[86:89], 0
	v_exp_f32_e32 v206, v206
	v_add_f32_e32 v133, v133, v190
	v_exp_f32_e32 v207, v207
	v_add_f32_e32 v135, v135, v191
	v_exp_f32_e32 v208, v208
	v_mfma_f32_32x32x16_bf16 v[48:63], v[160:163], v[86:89], 0
	v_add_f32_e32 v133, v133, v192
	v_exp_f32_e32 v209, v209
	v_add_f32_e32 v135, v135, v193
	v_exp_f32_e32 v210, v210
	v_add_f32_e32 v133, v133, v194
	v_mfma_f32_32x32x16_bf16 v[32:47], v[164:167], v[82:85], v[32:47]
	v_exp_f32_e32 v211, v211
	v_add_f32_e32 v135, v135, v195
	v_exp_f32_e32 v212, v212
	v_add_f32_e32 v133, v133, v196
	v_exp_f32_e32 v213, v213
	v_add_f32_e32 v135, v135, v197
	v_mfma_f32_32x32x16_bf16 v[48:63], v[168:171], v[82:85], v[48:63]
	s_waitcnt lgkmcnt(7)
	ds_read_b64_tr_b16 v[238:239], v134 offset:33280
	ds_read_b64_tr_b16 v[240:241], v134 offset:35328
	ds_read_b64_tr_b16 v[242:243], v134 offset:37376
	ds_read_b64_tr_b16 v[244:245], v134 offset:39424
	ds_read_b64_tr_b16 v[246:247], v134 offset:41472
	ds_read_b64_tr_b16 v[248:249], v134 offset:43520
	ds_read_b64_tr_b16 v[140:141], v134 offset:45568
	ds_read_b64_tr_b16 v[142:143], v134 offset:47616
	v_exp_f32_e32 v214, v214
	v_add_f32_e32 v133, v133, v198
	v_exp_f32_e32 v215, v215
	v_add_f32_e32 v135, v135, v199
	v_exp_f32_e32 v216, v216
	v_mfma_f32_32x32x16_bf16 v[32:47], v[172:175], v[90:93], v[32:47]
	v_add_f32_e32 v133, v133, v200
	v_exp_f32_e32 v217, v217
	v_add_f32_e32 v135, v135, v201
	v_exp_f32_e32 v218, v218
	v_add_f32_e32 v133, v133, v202
	v_mfma_f32_32x32x16_bf16 v[48:63], v[176:179], v[90:93], v[48:63]
	v_exp_f32_e32 v219, v219
	v_add_f32_e32 v135, v135, v203
	v_exp_f32_e32 v220, v220
	v_add_f32_e32 v133, v133, v204
	v_exp_f32_e32 v221, v221
	v_add_f32_e32 v135, v135, v205
	v_mfma_f32_32x32x16_bf16 v[32:47], v[180:183], v[94:97], v[32:47]
	v_add_f32_e32 v133, v133, v206
	v_add_f32_e32 v135, v135, v207
	v_add_f32_e32 v133, v133, v208
	v_add_f32_e32 v135, v135, v209
	v_add_f32_e32 v133, v133, v210
	v_mfma_f32_32x32x16_bf16 v[48:63], v[184:187], v[94:97], v[48:63]
	v_add_f32_e32 v135, v135, v211
	v_add_f32_e32 v133, v133, v212
	v_add_f32_e32 v135, v135, v213
	v_add_f32_e32 v133, v133, v214
	v_add_f32_e32 v135, v135, v215
	v_mfma_f32_32x32x16_bf16 v[32:47], v[64:67], v[98:101], v[32:47]
	v_add_f32_e32 v133, v133, v216
	v_add_f32_e32 v135, v135, v217
	v_add_f32_e32 v133, v133, v218
	v_add_f32_e32 v135, v135, v219
	v_add_f32_e32 v133, v133, v220
	v_add_f32_e32 v135, v135, v221
	v_mfma_f32_32x32x16_bf16 v[48:63], v[68:71], v[98:101], v[48:63]
	v_cvt_pk_bf16_f32 v190, v190, v191
	v_cvt_pk_bf16_f32 v191, v192, v193
	v_cvt_pk_bf16_f32 v192, v194, v195
	v_cvt_pk_bf16_f32 v193, v196, v197
	v_cvt_pk_bf16_f32 v194, v198, v199
	v_mfma_f32_32x32x16_bf16 v[32:47], v[72:75], v[102:105], v[32:47]
	v_cvt_pk_bf16_f32 v195, v200, v201
	v_cvt_pk_bf16_f32 v196, v202, v203
	v_cvt_pk_bf16_f32 v197, v204, v205
	v_cvt_pk_bf16_f32 v206, v206, v207
	v_cvt_pk_bf16_f32 v207, v208, v209
	v_mfma_f32_32x32x16_bf16 v[48:63], v[76:79], v[102:105], v[48:63]
	v_cvt_pk_bf16_f32 v208, v210, v211
	v_cvt_pk_bf16_f32 v209, v212, v213
	v_cvt_pk_bf16_f32 v210, v214, v215
	v_cvt_pk_bf16_f32 v211, v216, v217
	v_cvt_pk_bf16_f32 v212, v218, v219
	v_cvt_pk_bf16_f32 v213, v220, v221
	s_waitcnt lgkmcnt(0)
	s_waitcnt vmcnt(1)
	s_barrier
	ds_read_b128 v[156:159], v146 offset:16384
	ds_read_b128 v[160:163], v146 offset:24576
	ds_read_b128 v[164:167], v147 offset:16384
	ds_read_b128 v[168:171], v147 offset:24576
	ds_read_b128 v[172:175], v148 offset:16384
	ds_read_b128 v[176:179], v148 offset:24576
	ds_read_b128 v[180:183], v149 offset:16384
	ds_read_b128 v[184:187], v149 offset:24576
	ds_read_b128 v[64:67], v150 offset:16384
	ds_read_b128 v[68:71], v150 offset:24576
	ds_read_b128 v[72:75], v151 offset:16384
	ds_read_b128 v[76:79], v151 offset:24576
	v_mfma_f32_32x32x16_bf16 v[0:15], v[190:193], v[222:225], v[0:15]
	v_exp_f32_e32 v32, v32
	v_exp_f32_e32 v33, v33
	v_mfma_f32_32x32x16_bf16 v[0:15], v[194:197], v[226:229], v[0:15]
	v_exp_f32_e32 v34, v34
	v_exp_f32_e32 v35, v35
	v_mfma_f32_32x32x16_bf16 v[0:15], v[206:209], v[230:233], v[0:15]
	v_exp_f32_e32 v36, v36
	v_exp_f32_e32 v37, v37
	v_mfma_f32_32x32x16_bf16 v[0:15], v[210:213], v[234:237], v[0:15]
	v_exp_f32_e32 v38, v38
	v_exp_f32_e32 v39, v39
	v_mfma_f32_32x32x16_bf16 v[16:31], v[190:193], v[238:241], v[16:31]
	v_exp_f32_e32 v40, v40
	v_exp_f32_e32 v41, v41
	v_mfma_f32_32x32x16_bf16 v[16:31], v[194:197], v[242:245], v[16:31]
	v_exp_f32_e32 v42, v42
	v_exp_f32_e32 v43, v43
	v_mfma_f32_32x32x16_bf16 v[16:31], v[206:209], v[246:249], v[16:31]
	v_exp_f32_e32 v44, v44
	v_exp_f32_e32 v45, v45
	v_mfma_f32_32x32x16_bf16 v[16:31], v[210:213], v[140:143], v[16:31]
	v_exp_f32_e32 v46, v46
	v_exp_f32_e32 v47, v47
	s_waitcnt lgkmcnt(0)
; __device__ __forceinline__ void partialSM(f32x16& p0) {
; #pragma unroll
;   for (int r = 0; r < 16; ++r) p0[r] = __builtin_amdgcn_exp2f(p0[r]);
; }
; __device__ __forceinline__ void finishSM(f32x16& p0, f32x16& p1, float& l_reg, bf16x8& pa0, bf16x8& pa1, bf16x8& pa2, bf16x8& pa3) {
; #pragma unroll
;   for (int r = 0; r < 16; ++r) p1[r] = __builtin_amdgcn_exp2f(p1[r]);
;   float ps = 0;
; #pragma unroll
;   for (int r = 0; r < 16; ++r) ps += p0[r];
; #pragma unroll
;   for (int r = 0; r < 16; ++r) ps += p1[r];
;   l_reg += ps;
;     ...
;   PK4(p0, 0, pa0); PK4(p0, 8, pa1); PK4(p1, 0, pa2); PK4(p1, 8, pa3);
;     ...
; }
; template <int ND> __device__ __forceinline__ void qkt(f32x16& p0, f32x16& p1, const bf16* Ks, const bf16x8* qr, int r32, int hi) {
;   p0 = f32x16{}; p1 = f32x16{};
; #pragma unroll
;   for (int d0 = 0; d0 < ND; ++d0) { int cb = (d0 * 16 + hi * 8) * 2;
;     bf16x8 b0 = *reinterpret_cast<const bf16x8*>((const char*)Ks + KSWZ(r32, cb));
;     bf16x8 b1 = *reinterpret_cast<const bf16x8*>((const char*)Ks + KSWZ(32 + r32, cb));
;     p0 = __builtin_amdgcn_mfma_f32_32x32x16_bf16(b0, qr[d0], p0, 0, 0, 0);
;     p1 = __builtin_amdgcn_mfma_f32_32x32x16_bf16(b1, qr[d0], p1, 0, 0, 0); }
; }
; __device__ __forceinline__ int v_st(int k, int c) { const int kk = (k & ~0xC) | ((k & 4) << 1) | ((k & 8) >> 1); return ((kk >> 3) * 4 + (c >> 5)) * 512 + ((kk & 7) * 32 + (c & 31)) * 2; }
; __device__ __forceinline__ int v_rd_base(int lane) { return ((lane & 3) << 3) | (((lane >> 2) & 3) << 6) | (((lane >> 4) & 1) << 5) | (((lane >> 5) & 1) << 8); }
; template <int OFF> __device__ __forceinline__ s16x4 tr_read(int vb) {
;   s16x4 r; asm volatile("ds_read_b64_tr_b16 %0, %1 offset:%2" : "=&v"(r) : "v"(vb), "i"(OFF) : "memory"); return r;
; }
; template <bool SHIFT> __device__ __forceinline__ void attn_dense_body(const bf16* __restrict__ Qb, const bf16* __restrict__ Kh, const bf16* __restrict__ Vh, bf16* __restrict__ Ob, int seq, char* lds, LAS unsigned char* ldsl, float negB, const float* __restrict__ gq, int qpos0) {
;     ...
;   SBAR(); qkt<SHIFT ? 7 : 6>(pB0, pB1, (bf16*)((char*)K_lds + bk * SHM_K), qr, r32, hi);
;   finishSM(pA0, pA1, l_reg, pa0, pa1, pa2, pa3); SBAR();
;   pv_d0(o, vb0 + bv * (int)SHM_V, pa0, pa1, pa2, pa3); partialSM(pB0);
;   ROT();
;   finishSM(pB0, pB1, l_reg, pa0, pa1, pa2, pa3); SBAR();
;   pv_d0(o, vb0 + bv * (int)SHM_V, pa0, pa1, pa2, pa3);
	ds_read_b64_tr_b16 v[222:223], v134 offset:0
	ds_read_b64_tr_b16 v[224:225], v134 offset:2048
	ds_read_b64_tr_b16 v[226:227], v134 offset:4096
	ds_read_b64_tr_b16 v[228:229], v134 offset:6144
	ds_read_b64_tr_b16 v[230:231], v134 offset:8192
	ds_read_b64_tr_b16 v[232:233], v134 offset:10240
	ds_read_b64_tr_b16 v[234:235], v134 offset:12288
	ds_read_b64_tr_b16 v[236:237], v134 offset:14336
	v_mfma_f32_32x32x16_bf16 v[190:205], v[156:159], v[86:89], 0
	v_exp_f32_e32 v48, v48
	v_add_f32_e32 v133, v133, v32
	v_exp_f32_e32 v49, v49
	v_add_f32_e32 v135, v135, v33
	v_exp_f32_e32 v50, v50
	v_mfma_f32_32x32x16_bf16 v[206:221], v[160:163], v[86:89], 0
	v_add_f32_e32 v133, v133, v34
	v_exp_f32_e32 v51, v51
	v_add_f32_e32 v135, v135, v35
	v_exp_f32_e32 v52, v52
	v_add_f32_e32 v133, v133, v36
	v_mfma_f32_32x32x16_bf16 v[190:205], v[164:167], v[82:85], v[190:205]
	v_exp_f32_e32 v53, v53
	v_add_f32_e32 v135, v135, v37
	v_exp_f32_e32 v54, v54
	v_add_f32_e32 v133, v133, v38
	v_exp_f32_e32 v55, v55
	v_add_f32_e32 v135, v135, v39
	v_mfma_f32_32x32x16_bf16 v[206:221], v[168:171], v[82:85], v[206:221]
	s_waitcnt lgkmcnt(7)
	ds_read_b64_tr_b16 v[238:239], v134 offset:512
	ds_read_b64_tr_b16 v[240:241], v134 offset:2560
	ds_read_b64_tr_b16 v[242:243], v134 offset:4608
	ds_read_b64_tr_b16 v[244:245], v134 offset:6656
	ds_read_b64_tr_b16 v[246:247], v134 offset:8704
	ds_read_b64_tr_b16 v[248:249], v134 offset:10752
	ds_read_b64_tr_b16 v[140:141], v134 offset:12800
	ds_read_b64_tr_b16 v[142:143], v134 offset:14848
	v_exp_f32_e32 v56, v56
	v_add_f32_e32 v133, v133, v40
	v_exp_f32_e32 v57, v57
	v_add_f32_e32 v135, v135, v41
	v_exp_f32_e32 v58, v58
	v_mfma_f32_32x32x16_bf16 v[190:205], v[172:175], v[90:93], v[190:205]
	v_add_f32_e32 v133, v133, v42
	v_exp_f32_e32 v59, v59
	v_add_f32_e32 v135, v135, v43
	v_exp_f32_e32 v60, v60
	v_add_f32_e32 v133, v133, v44
	v_mfma_f32_32x32x16_bf16 v[206:221], v[176:179], v[90:93], v[206:221]
	v_exp_f32_e32 v61, v61
	v_add_f32_e32 v135, v135, v45
	v_exp_f32_e32 v62, v62
	v_add_f32_e32 v133, v133, v46
	v_exp_f32_e32 v63, v63
	v_add_f32_e32 v135, v135, v47
	v_mfma_f32_32x32x16_bf16 v[190:205], v[180:183], v[94:97], v[190:205]
	v_add_f32_e32 v133, v133, v48
	v_add_f32_e32 v135, v135, v49
	v_add_f32_e32 v133, v133, v50
	v_add_f32_e32 v135, v135, v51
	v_add_f32_e32 v133, v133, v52
	v_mfma_f32_32x32x16_bf16 v[206:221], v[184:187], v[94:97], v[206:221]
	v_add_f32_e32 v135, v135, v53
	v_add_f32_e32 v133, v133, v54
	v_add_f32_e32 v135, v135, v55
	v_add_f32_e32 v133, v133, v56
	v_add_f32_e32 v135, v135, v57
	v_mfma_f32_32x32x16_bf16 v[190:205], v[64:67], v[98:101], v[190:205]
	v_add_f32_e32 v133, v133, v58
	v_add_f32_e32 v135, v135, v59
	v_add_f32_e32 v133, v133, v60
	v_add_f32_e32 v135, v135, v61
	v_add_f32_e32 v133, v133, v62
	v_add_f32_e32 v135, v135, v63
	v_mfma_f32_32x32x16_bf16 v[206:221], v[68:71], v[98:101], v[206:221]
	v_cvt_pk_bf16_f32 v32, v32, v33
	v_cvt_pk_bf16_f32 v33, v34, v35
	v_cvt_pk_bf16_f32 v34, v36, v37
	v_cvt_pk_bf16_f32 v35, v38, v39
	v_cvt_pk_bf16_f32 v36, v40, v41
	v_mfma_f32_32x32x16_bf16 v[190:205], v[72:75], v[102:105], v[190:205]
	v_cvt_pk_bf16_f32 v37, v42, v43
	v_cvt_pk_bf16_f32 v38, v44, v45
	v_cvt_pk_bf16_f32 v39, v46, v47
	v_cvt_pk_bf16_f32 v48, v48, v49
	v_cvt_pk_bf16_f32 v49, v50, v51
	v_mfma_f32_32x32x16_bf16 v[206:221], v[76:79], v[102:105], v[206:221]
	v_cvt_pk_bf16_f32 v50, v52, v53
	v_cvt_pk_bf16_f32 v51, v54, v55
	v_cvt_pk_bf16_f32 v52, v56, v57
	v_cvt_pk_bf16_f32 v53, v58, v59
	v_cvt_pk_bf16_f32 v54, v60, v61
	v_cvt_pk_bf16_f32 v55, v62, v63
	s_waitcnt lgkmcnt(0)
	s_waitcnt vmcnt(0)
	s_barrier
	s_nop 7
	s_nop 3
	v_mfma_f32_32x32x16_bf16 v[0:15], v[32:35], v[222:225], v[0:15]
	v_exp_f32_e32 v190, v190
	v_exp_f32_e32 v191, v191
	v_mfma_f32_32x32x16_bf16 v[0:15], v[36:39], v[226:229], v[0:15]
	v_exp_f32_e32 v192, v192
	v_exp_f32_e32 v193, v193
	v_mfma_f32_32x32x16_bf16 v[0:15], v[48:51], v[230:233], v[0:15]
	v_exp_f32_e32 v194, v194
	v_exp_f32_e32 v195, v195
	v_mfma_f32_32x32x16_bf16 v[0:15], v[52:55], v[234:237], v[0:15]
	v_exp_f32_e32 v196, v196
	v_exp_f32_e32 v197, v197
	v_mfma_f32_32x32x16_bf16 v[16:31], v[32:35], v[238:241], v[16:31]
	v_exp_f32_e32 v198, v198
	v_exp_f32_e32 v199, v199
	v_mfma_f32_32x32x16_bf16 v[16:31], v[36:39], v[242:245], v[16:31]
	v_exp_f32_e32 v200, v200
	v_exp_f32_e32 v201, v201
	v_mfma_f32_32x32x16_bf16 v[16:31], v[48:51], v[246:249], v[16:31]
	v_exp_f32_e32 v202, v202
	v_exp_f32_e32 v203, v203
	v_mfma_f32_32x32x16_bf16 v[16:31], v[52:55], v[140:143], v[16:31]
	v_exp_f32_e32 v204, v204
	v_exp_f32_e32 v205, v205
	s_waitcnt lgkmcnt(0)
	ds_read_b64_tr_b16 v[222:223], v134 offset:16384
	ds_read_b64_tr_b16 v[224:225], v134 offset:18432
	ds_read_b64_tr_b16 v[226:227], v134 offset:20480
	ds_read_b64_tr_b16 v[228:229], v134 offset:22528
	ds_read_b64_tr_b16 v[230:231], v134 offset:24576
	ds_read_b64_tr_b16 v[232:233], v134 offset:26624
	ds_read_b64_tr_b16 v[234:235], v134 offset:28672
	ds_read_b64_tr_b16 v[236:237], v134 offset:30720
	s_nop 3
	s_waitcnt lgkmcnt(7)
; #define SBAR() __builtin_amdgcn_sched_barrier(0)
; __device__ __forceinline__ int crow(int r, int hi) { return (r & 3) + 8 * (r >> 2) + 4 * hi; }
; template <bool SHIFT> __device__ __forceinline__ void attn_dense_body(const bf16* __restrict__ Qb, const bf16* __restrict__ Kh, const bf16* __restrict__ Vh, bf16* __restrict__ Ob, int seq, char* lds, LAS unsigned char* ldsl, float negB, const float* __restrict__ gq, int qpos0) {
;     ...
;   finishSM(pB0, pB1, l_reg, pa0, pa1, pa2, pa3); SBAR();
;   pv_d0(o, vb0 + bv * (int)SHM_V, pa0, pa1, pa2, pa3);
;     ...
;   { auto rr = __builtin_amdgcn_permlane32_swap(__float_as_uint(l_reg), __float_as_uint(l_reg), false, false); l_reg = __uint_as_float(rr[0]) + __uint_as_float(rr[1]); }
;   if (hi == 0) li_l[r32] = l_reg; asm volatile("s_waitcnt lgkmcnt(0)" ::: "memory");
;   float rli[16];
; #pragma unroll
;   for (int r = 0; r < 16; ++r) rli[r] = __builtin_amdgcn_rcpf(li_l[crow(r, hi)]);
	ds_read_b64_tr_b16 v[238:239], v134 offset:16896
	ds_read_b64_tr_b16 v[240:241], v134 offset:18944
	ds_read_b64_tr_b16 v[242:243], v134 offset:20992
	ds_read_b64_tr_b16 v[244:245], v134 offset:23040
	ds_read_b64_tr_b16 v[246:247], v134 offset:25088
	ds_read_b64_tr_b16 v[248:249], v134 offset:27136
	ds_read_b64_tr_b16 v[140:141], v134 offset:29184
	ds_read_b64_tr_b16 v[142:143], v134 offset:31232
	v_exp_f32_e32 v206, v206
	v_add_f32_e32 v133, v133, v190
	v_exp_f32_e32 v207, v207
	v_add_f32_e32 v135, v135, v191
	v_exp_f32_e32 v208, v208
	v_add_f32_e32 v133, v133, v192
	v_exp_f32_e32 v209, v209
	v_add_f32_e32 v135, v135, v193
	v_exp_f32_e32 v210, v210
	v_add_f32_e32 v133, v133, v194
	v_exp_f32_e32 v211, v211
	v_add_f32_e32 v135, v135, v195
	v_exp_f32_e32 v212, v212
	v_add_f32_e32 v133, v133, v196
	v_exp_f32_e32 v213, v213
	v_add_f32_e32 v135, v135, v197
	v_exp_f32_e32 v214, v214
	v_add_f32_e32 v133, v133, v198
	v_exp_f32_e32 v215, v215
	v_add_f32_e32 v135, v135, v199
	v_exp_f32_e32 v216, v216
	v_add_f32_e32 v133, v133, v200
	v_exp_f32_e32 v217, v217
	v_add_f32_e32 v135, v135, v201
	v_exp_f32_e32 v218, v218
	v_add_f32_e32 v133, v133, v202
	v_exp_f32_e32 v219, v219
	v_add_f32_e32 v135, v135, v203
	v_exp_f32_e32 v220, v220
	v_add_f32_e32 v133, v133, v204
	v_exp_f32_e32 v221, v221
	v_add_f32_e32 v135, v135, v205
	v_add_f32_e32 v133, v133, v206
	v_add_f32_e32 v135, v135, v207
	v_add_f32_e32 v133, v133, v208
	v_add_f32_e32 v135, v135, v209
	v_add_f32_e32 v133, v133, v210
	v_add_f32_e32 v135, v135, v211
	v_add_f32_e32 v133, v133, v212
	v_add_f32_e32 v135, v135, v213
	v_add_f32_e32 v133, v133, v214
	v_add_f32_e32 v135, v135, v215
	v_add_f32_e32 v133, v133, v216
	v_add_f32_e32 v135, v135, v217
	v_add_f32_e32 v133, v133, v218
	v_add_f32_e32 v135, v135, v219
	v_add_f32_e32 v133, v133, v220
	v_add_f32_e32 v135, v135, v221
	v_cvt_pk_bf16_f32 v190, v190, v191
	v_cvt_pk_bf16_f32 v191, v192, v193
	v_cvt_pk_bf16_f32 v192, v194, v195
	v_cvt_pk_bf16_f32 v193, v196, v197
	v_cvt_pk_bf16_f32 v194, v198, v199
	v_cvt_pk_bf16_f32 v195, v200, v201
	v_cvt_pk_bf16_f32 v196, v202, v203
	v_cvt_pk_bf16_f32 v197, v204, v205
	v_cvt_pk_bf16_f32 v206, v206, v207
	v_cvt_pk_bf16_f32 v207, v208, v209
	v_cvt_pk_bf16_f32 v208, v210, v211
	v_cvt_pk_bf16_f32 v209, v212, v213
	v_cvt_pk_bf16_f32 v210, v214, v215
	v_cvt_pk_bf16_f32 v211, v216, v217
	v_cvt_pk_bf16_f32 v212, v218, v219
	v_cvt_pk_bf16_f32 v213, v220, v221
	s_waitcnt lgkmcnt(0)
	s_nop 7
	s_nop 3
	v_mfma_f32_32x32x16_bf16 v[0:15], v[190:193], v[222:225], v[0:15]
	v_mfma_f32_32x32x16_bf16 v[0:15], v[194:197], v[226:229], v[0:15]
	v_mfma_f32_32x32x16_bf16 v[0:15], v[206:209], v[230:233], v[0:15]
	v_mfma_f32_32x32x16_bf16 v[0:15], v[210:213], v[234:237], v[0:15]
	v_mfma_f32_32x32x16_bf16 v[16:31], v[190:193], v[238:241], v[16:31]
	v_mfma_f32_32x32x16_bf16 v[16:31], v[194:197], v[242:245], v[16:31]
	v_mfma_f32_32x32x16_bf16 v[16:31], v[206:209], v[246:249], v[16:31]
	v_mfma_f32_32x32x16_bf16 v[16:31], v[210:213], v[140:143], v[16:31]
	v_add_f32_e32 v32, v133, v135
	s_nop 0
	v_mov_b32_e32 v33, v32
	s_nop 1
	v_permlane32_swap_b32_e32 v32, v33
	s_and_saveexec_b64 s[4:5], s[6:7]
	v_add_f32_e32 v32, v32, v33
	ds_write_b32 v153, v32
	s_or_b64 exec, exec, s[4:5]
	s_waitcnt lgkmcnt(0)
	v_add_u32_e32 v40, v113, v117
	ds_read_b128 v[32:35], v40
	ds_read_b128 v[36:39], v40 offset:32
	s_waitcnt lgkmcnt(1)
	v_rcp_f32_e32 v41, v32
	v_rcp_f32_e32 v42, v33
	v_rcp_f32_e32 v43, v34
	v_rcp_f32_e32 v44, v35
	ds_read_b128 v[32:35], v40 offset:64
	s_waitcnt lgkmcnt(1)
	v_rcp_f32_e32 v45, v36
	v_rcp_f32_e32 v46, v37
	v_rcp_f32_e32 v47, v38
	v_rcp_f32_e32 v48, v39
	ds_read_b128 v[36:39], v40 offset:96
	s_waitcnt lgkmcnt(1)
; __device__ __forceinline__ int crow(int r, int hi) { return (r & 3) + 8 * (r >> 2) + 4 * hi; }
; __device__ __forceinline__ unsigned cvtpk(float lo, float hi) { unsigned r; asm volatile("v_cvt_pk_bf16_f32 %0, %1, %2" : "=v"(r) : "v"(lo), "v"(hi)); return r; }
; template <bool SHIFT> __device__ __forceinline__ void attn_dense_body(const bf16* __restrict__ Qb, const bf16* __restrict__ Kh, const bf16* __restrict__ Vh, bf16* __restrict__ Ob, int seq, char* lds, LAS unsigned char* ldsl, float negB, const float* __restrict__ gq, int qpos0) {
;     ...
;   float rli[16];
; #pragma unroll
;   for (int r = 0; r < 16; ++r) rli[r] = __builtin_amdgcn_rcpf(li_l[crow(r, hi)]);
;   bf16* Ow = Ob + (long)(wid * QBLK) * LDO;
; #pragma unroll
;   for (int r = 0; r < 16; ++r) { int orow = crow(r, hi);
; #pragma unroll
;     for (int d0 = 0; d0 < 2; ++d0) Ow[(long)orow * LDO + d0 * 32 + r32] = (bf16)(cvtpk(o[d0][r] * rli[r], 0.f) & 0xffffu); }
;   __syncthreads();
	v_rcp_f32_e32 v40, v32
	v_rcp_f32_e32 v49, v33
	v_lshlrev_b32_e32 v32, 1, v116
	v_mov_b32_e32 v33, v81
	v_rcp_f32_e32 v50, v34
	v_rcp_f32_e32 v51, v35
	v_lshl_add_u64 v[32:33], s[38:39], 0, v[32:33]
	v_lshlrev_b32_e32 v34, 1, v108
	v_mov_b32_e32 v35, v81
	v_lshl_add_u64 v[32:33], v[32:33], 0, v[34:35]
	v_mul_f32_e32 v0, v0, v41
	v_lshl_add_u64 v[32:33], v[32:33], 0, v[118:119]
	v_cvt_pk_bf16_f32 v0, v0, v81
	global_store_short v[32:33], v0, off
	v_mul_f32_e32 v0, v16, v41
	v_cvt_pk_bf16_f32 v0, v0, v81
	global_store_short v[32:33], v0, off offset:64
	v_mul_f32_e32 v0, v1, v42
	v_cvt_pk_bf16_f32 v0, v0, v81
	global_store_short v[32:33], v0, off offset:2048
	v_mul_f32_e32 v0, v17, v42
	v_cvt_pk_bf16_f32 v0, v0, v81
	global_store_short v[32:33], v0, off offset:2112
	v_mul_f32_e32 v0, v2, v43
	v_cvt_pk_bf16_f32 v2, v0, v81
	v_add_co_u32_e32 v0, vcc, s47, v32
	s_waitcnt lgkmcnt(0)
	v_rcp_f32_e32 v36, v36
	v_addc_co_u32_e32 v1, vcc, 0, v33, vcc
	global_store_short v[0:1], v2, off
	v_mul_f32_e32 v2, v18, v43
	v_cvt_pk_bf16_f32 v2, v2, v81
	global_store_short v[0:1], v2, off offset:64
	v_mul_f32_e32 v2, v3, v44
	v_cvt_pk_bf16_f32 v2, v2, v81
	global_store_short v[0:1], v2, off offset:2048
	v_mul_f32_e32 v2, v19, v44
	v_cvt_pk_bf16_f32 v2, v2, v81
	global_store_short v[0:1], v2, off offset:2112
	v_mul_f32_e32 v0, v4, v45
	v_cvt_pk_bf16_f32 v4, v0, v81
	v_add_co_u32_e32 v0, vcc, s41, v32
	v_rcp_f32_e32 v37, v37
	s_nop 0
	v_addc_co_u32_e32 v1, vcc, 0, v33, vcc
	v_add_co_u32_e32 v2, vcc, s48, v32
	v_rcp_f32_e32 v38, v38
	s_nop 0
	v_addc_co_u32_e32 v3, vcc, 0, v33, vcc
	global_store_short v[2:3], v4, off offset:-4096
	v_mul_f32_e32 v4, v20, v45
	v_cvt_pk_bf16_f32 v4, v4, v81
	global_store_short v[0:1], v4, off offset:64
	v_mul_f32_e32 v4, v5, v46
	v_cvt_pk_bf16_f32 v4, v4, v81
	global_store_short v[0:1], v4, off offset:2048
	v_mul_f32_e32 v4, v21, v46
	v_cvt_pk_bf16_f32 v4, v4, v81
	global_store_short v[0:1], v4, off offset:2112
	v_mul_f32_e32 v0, v6, v47
	v_cvt_pk_bf16_f32 v0, v0, v81
	global_store_short v[2:3], v0, off
	v_mul_f32_e32 v0, v22, v47
	v_cvt_pk_bf16_f32 v0, v0, v81
	global_store_short v[2:3], v0, off offset:64
	v_mul_f32_e32 v0, v7, v48
	v_cvt_pk_bf16_f32 v0, v0, v81
	global_store_short v[2:3], v0, off offset:2048
	v_mul_f32_e32 v0, v23, v48
	v_cvt_pk_bf16_f32 v0, v0, v81
	global_store_short v[2:3], v0, off offset:2112
	v_mul_f32_e32 v0, v8, v40
	v_cvt_pk_bf16_f32 v4, v0, v81
	v_add_co_u32_e32 v0, vcc, s49, v32
	v_rcp_f32_e32 v39, v39
	s_nop 0
	v_addc_co_u32_e32 v1, vcc, 0, v33, vcc
	v_add_co_u32_e32 v2, vcc, s54, v32
	s_nop 1
	v_addc_co_u32_e32 v3, vcc, 0, v33, vcc
	global_store_short v[2:3], v4, off offset:-4096
	v_mul_f32_e32 v4, v24, v40
	v_cvt_pk_bf16_f32 v4, v4, v81
	global_store_short v[0:1], v4, off offset:64
	v_mul_f32_e32 v4, v9, v49
	v_cvt_pk_bf16_f32 v4, v4, v81
	global_store_short v[0:1], v4, off offset:2048
	v_mul_f32_e32 v4, v25, v49
	v_cvt_pk_bf16_f32 v4, v4, v81
	global_store_short v[0:1], v4, off offset:2112
	v_mul_f32_e32 v0, v10, v50
	v_cvt_pk_bf16_f32 v0, v0, v81
	global_store_short v[2:3], v0, off
	v_mul_f32_e32 v0, v26, v50
	v_cvt_pk_bf16_f32 v0, v0, v81
	global_store_short v[2:3], v0, off offset:64
	v_mul_f32_e32 v0, v11, v51
	v_cvt_pk_bf16_f32 v0, v0, v81
	global_store_short v[2:3], v0, off offset:2048
	v_mul_f32_e32 v0, v27, v51
	v_cvt_pk_bf16_f32 v0, v0, v81
	global_store_short v[2:3], v0, off offset:2112
	v_mul_f32_e32 v0, v12, v36
	v_cvt_pk_bf16_f32 v4, v0, v81
	v_add_co_u32_e32 v0, vcc, s45, v32
	s_nop 1
	v_addc_co_u32_e32 v1, vcc, 0, v33, vcc
	v_add_co_u32_e32 v2, vcc, s55, v32
	s_nop 1
	v_addc_co_u32_e32 v3, vcc, 0, v33, vcc
	global_store_short v[2:3], v4, off offset:-4096
	v_mul_f32_e32 v4, v28, v36
	v_cvt_pk_bf16_f32 v4, v4, v81
	global_store_short v[0:1], v4, off offset:64
	v_mul_f32_e32 v4, v13, v37
	v_cvt_pk_bf16_f32 v4, v4, v81
	global_store_short v[0:1], v4, off offset:2048
	v_mul_f32_e32 v4, v29, v37
	v_cvt_pk_bf16_f32 v4, v4, v81
	global_store_short v[0:1], v4, off offset:2112
	v_mul_f32_e32 v0, v14, v38
	v_cvt_pk_bf16_f32 v0, v0, v81
	global_store_short v[2:3], v0, off
	v_mul_f32_e32 v0, v30, v38
	v_cvt_pk_bf16_f32 v0, v0, v81
	global_store_short v[2:3], v0, off offset:64
	v_mul_f32_e32 v0, v15, v39
	v_cvt_pk_bf16_f32 v0, v0, v81
	global_store_short v[2:3], v0, off offset:2048
	v_mul_f32_e32 v0, v31, v39
	v_cvt_pk_bf16_f32 v0, v0, v81
	global_store_short v[2:3], v0, off offset:2112
	s_barrier
	s_branch .LBB0_1590
